# speedup vs baseline: 1.0037x; 1.0037x over previous
; #define MFMA16(a, b, c) __builtin_amdgcn_mfma_f32_16x16x32_bf16(a, b, c, 0, 0, 0)
; #define MFMA8(a, b, c) __builtin_amdgcn_mfma_f32_16x16x32_fp8_fp8(a, b, c, 0, 0, 0)
; template <bool FP8>
; __device__ __forceinline__ void gemm_tile_256(const u16* __restrict__ A, int lda, const u16* __restrict__ Bt, int ldb,
;                                               int K, char* smem, f32x4 (&acc)[8][4]) {
;     ...
; #pragma unroll
;     for (int kk = 0; kk < 2; ++kk) {
;       const int ch = ((kk * 4 + fq) ^ sw) << 4;
;       bf16x8 bfr[4], af[8];
; #pragma unroll
;       for (int n = 0; n < 4; ++n) bfr[n] = *(const bf16x8*)(smem + brow + n * 2048 + ch);
; #pragma unroll
;       for (int m = 0; m < 8; ++m) af[m] = *(const bf16x8*)(smem + arow + m * 2048 + ch);
;       __builtin_amdgcn_sched_group_barrier(0x100, 12, 0);
;       __builtin_amdgcn_sched_group_barrier(0x008, 32, 0);
; #pragma unroll
;       for (int m = 0; m < 8; ++m)
; #pragma unroll
;         for (int n = 0; n < 4; ++n) {
;           if (FP8) {
;             union { bf16x8 v; long l[2]; } ua, ub;
;             ua.v = af[m]; ub.v = bfr[n];
;             acc[m][n] = MFMA8(ub.l[0], ua.l[0], acc[m][n]);
;             acc[m][n] = MFMA8(ub.l[1], ua.l[1], acc[m][n]);
;           } else {
;             acc[m][n] = MFMA16(bfr[n], af[m], acc[m][n]);
;           }
;         }
.LBB0_127:
	s_setprio 2
	v_add_u32_e32 v185, v180, v184
	s_waitcnt lgkmcnt(7)
	v_mfma_f32_16x16x32_bf16 v[112:115], v[198:201], v[202:205], v[112:115]
	s_add_u32 s10, s10, 0x80
	s_addc_u32 s11, s11, 0
	s_add_i32 s5, s5, 1
	s_waitcnt lgkmcnt(6)
	v_mfma_f32_16x16x32_bf16 v[96:99], v[198:201], v[206:209], v[96:99]
	s_cmpk_lg_i32 s10, 0x1000
	s_waitcnt lgkmcnt(5)
	v_mfma_f32_16x16x32_bf16 v[80:83], v[198:201], v[210:213], v[80:83]
	s_waitcnt lgkmcnt(4)
	v_mfma_f32_16x16x32_bf16 v[64:67], v[198:201], v[224:227], v[64:67]
	s_waitcnt lgkmcnt(3)
	v_mfma_f32_16x16x32_bf16 v[48:51], v[198:201], v[236:239], v[48:51]
	s_waitcnt lgkmcnt(2)
	v_mfma_f32_16x16x32_bf16 v[32:35], v[198:201], v[240:243], v[32:35]
	s_waitcnt lgkmcnt(1)
	v_mfma_f32_16x16x32_bf16 v[16:19], v[198:201], v[244:247], v[16:19]
	s_waitcnt lgkmcnt(0)
	v_mfma_f32_16x16x32_bf16 v[0:3], v[198:201], v[248:251], v[0:3]
	ds_read_b128 v[198:201], v185 offset:38912
	v_mfma_f32_16x16x32_bf16 v[116:119], v[194:197], v[202:205], v[116:119]
	v_mfma_f32_16x16x32_bf16 v[100:103], v[194:197], v[206:209], v[100:103]
	v_mfma_f32_16x16x32_bf16 v[84:87], v[194:197], v[210:213], v[84:87]
	v_mfma_f32_16x16x32_bf16 v[68:71], v[194:197], v[224:227], v[68:71]
	v_mfma_f32_16x16x32_bf16 v[52:55], v[194:197], v[236:239], v[52:55]
	v_mfma_f32_16x16x32_bf16 v[36:39], v[194:197], v[240:243], v[36:39]
	v_mfma_f32_16x16x32_bf16 v[20:23], v[194:197], v[244:247], v[20:23]
	v_mfma_f32_16x16x32_bf16 v[4:7], v[194:197], v[248:251], v[4:7]
	ds_read_b128 v[194:197], v185 offset:36864
	v_mfma_f32_16x16x32_bf16 v[120:123], v[190:193], v[202:205], v[120:123]
	v_mfma_f32_16x16x32_bf16 v[104:107], v[190:193], v[206:209], v[104:107]
	v_mfma_f32_16x16x32_bf16 v[88:91], v[190:193], v[210:213], v[88:91]
	v_mfma_f32_16x16x32_bf16 v[72:75], v[190:193], v[224:227], v[72:75]
	v_mfma_f32_16x16x32_bf16 v[56:59], v[190:193], v[236:239], v[56:59]
	v_mfma_f32_16x16x32_bf16 v[40:43], v[190:193], v[240:243], v[40:43]
	v_mfma_f32_16x16x32_bf16 v[24:27], v[190:193], v[244:247], v[24:27]
	v_mfma_f32_16x16x32_bf16 v[8:11], v[190:193], v[248:251], v[8:11]
	ds_read_b128 v[190:193], v185 offset:34816
	v_mfma_f32_16x16x32_bf16 v[124:127], v[186:189], v[202:205], v[124:127]
	v_mfma_f32_16x16x32_bf16 v[108:111], v[186:189], v[206:209], v[108:111]
	v_mfma_f32_16x16x32_bf16 v[92:95], v[186:189], v[210:213], v[92:95]
	v_mfma_f32_16x16x32_bf16 v[76:79], v[186:189], v[224:227], v[76:79]
	v_mfma_f32_16x16x32_bf16 v[60:63], v[186:189], v[236:239], v[60:63]
	v_mfma_f32_16x16x32_bf16 v[44:47], v[186:189], v[240:243], v[44:47]
	v_mfma_f32_16x16x32_bf16 v[28:31], v[186:189], v[244:247], v[28:31]
	v_mfma_f32_16x16x32_bf16 v[12:15], v[186:189], v[248:251], v[12:15]
	ds_read_b128 v[186:189], v185 offset:32768
	v_add_u32_e32 v185, v181, v184
	ds_read_b128 v[202:205], v185
	ds_read_b128 v[206:209], v185 offset:2048
	ds_read_b128 v[210:213], v185 offset:4096
	ds_read_b128 v[224:227], v185 offset:6144
	ds_read_b128 v[236:239], v185 offset:8192
	ds_read_b128 v[240:243], v185 offset:10240
	ds_read_b128 v[244:247], v185 offset:12288
	ds_read_b128 v[248:251], v185 offset:14336
	s_waitcnt lgkmcnt(7)
	v_mfma_f32_16x16x32_bf16 v[124:127], v[186:189], v[202:205], v[124:127]
	v_mfma_f32_16x16x32_bf16 v[120:123], v[190:193], v[202:205], v[120:123]
	v_mfma_f32_16x16x32_bf16 v[116:119], v[194:197], v[202:205], v[116:119]
	v_mfma_f32_16x16x32_bf16 v[112:115], v[198:201], v[202:205], v[112:115]
	s_waitcnt lgkmcnt(6)
	v_mfma_f32_16x16x32_bf16 v[108:111], v[186:189], v[206:209], v[108:111]
	v_mfma_f32_16x16x32_bf16 v[104:107], v[190:193], v[206:209], v[104:107]
	v_mfma_f32_16x16x32_bf16 v[100:103], v[194:197], v[206:209], v[100:103]
	v_mfma_f32_16x16x32_bf16 v[96:99], v[198:201], v[206:209], v[96:99]
	s_waitcnt lgkmcnt(5)
	v_mfma_f32_16x16x32_bf16 v[92:95], v[186:189], v[210:213], v[92:95]
	v_mfma_f32_16x16x32_bf16 v[88:91], v[190:193], v[210:213], v[88:91]
	v_mfma_f32_16x16x32_bf16 v[84:87], v[194:197], v[210:213], v[84:87]
	v_mfma_f32_16x16x32_bf16 v[80:83], v[198:201], v[210:213], v[80:83]
	s_waitcnt lgkmcnt(4)
	v_mfma_f32_16x16x32_bf16 v[76:79], v[186:189], v[224:227], v[76:79]
	v_mfma_f32_16x16x32_bf16 v[72:75], v[190:193], v[224:227], v[72:75]
	v_mfma_f32_16x16x32_bf16 v[68:71], v[194:197], v[224:227], v[68:71]
	v_mfma_f32_16x16x32_bf16 v[64:67], v[198:201], v[224:227], v[64:67]
	s_waitcnt lgkmcnt(3)
	v_mfma_f32_16x16x32_bf16 v[60:63], v[186:189], v[236:239], v[60:63]
	v_mfma_f32_16x16x32_bf16 v[56:59], v[190:193], v[236:239], v[56:59]
	v_mfma_f32_16x16x32_bf16 v[52:55], v[194:197], v[236:239], v[52:55]
	v_mfma_f32_16x16x32_bf16 v[48:51], v[198:201], v[236:239], v[48:51]
	s_waitcnt lgkmcnt(2)
	v_mfma_f32_16x16x32_bf16 v[44:47], v[186:189], v[240:243], v[44:47]
	v_mfma_f32_16x16x32_bf16 v[40:43], v[190:193], v[240:243], v[40:43]
	v_mfma_f32_16x16x32_bf16 v[36:39], v[194:197], v[240:243], v[36:39]
	v_mfma_f32_16x16x32_bf16 v[32:35], v[198:201], v[240:243], v[32:35]
	s_waitcnt lgkmcnt(1)
	v_mfma_f32_16x16x32_bf16 v[28:31], v[186:189], v[244:247], v[28:31]
	v_mfma_f32_16x16x32_bf16 v[24:27], v[190:193], v[244:247], v[24:27]
	v_mfma_f32_16x16x32_bf16 v[20:23], v[194:197], v[244:247], v[20:23]
	v_mfma_f32_16x16x32_bf16 v[16:19], v[198:201], v[244:247], v[16:19]
	s_waitcnt lgkmcnt(0)
	v_mfma_f32_16x16x32_bf16 v[12:15], v[186:189], v[248:251], v[12:15]
	v_mfma_f32_16x16x32_bf16 v[8:11], v[190:193], v[248:251], v[8:11]
	v_mfma_f32_16x16x32_bf16 v[4:7], v[194:197], v[248:251], v[4:7]
	v_mfma_f32_16x16x32_bf16 v[0:3], v[198:201], v[248:251], v[0:3]
	s_cbranch_scc0 .LBB0_130
; template <bool FP8>
; __device__ __forceinline__ void gemm_tile_256(const u16* __restrict__ A, int lda, const u16* __restrict__ Bt, int ldb,
;                                               int K, char* smem, f32x4 (&acc)[8][4]) {
;     ...
;   for (int kt = 0; kt < nk; ++kt) {
;     __syncthreads();
; #pragma unroll
;     for (int q = 0; q < 8; ++q) *(u32x4*)(smem + wofs + q * 4096) = ra[q];
; #pragma unroll
;     for (int q = 0; q < 4; ++q) *(u32x4*)(smem + 32768 + wofs + q * 4096) = rb[q];
;     __syncthreads();
;     if (kt + 1 < nk) {
;       const int k0 = (kt + 1) << 6;
; #pragma unroll
;       for (int q = 0; q < 8; ++q) ra[q] = *(const u32x4*)(ag + (size_t)q * 32 * lda + k0);
; #pragma unroll
;       for (int q = 0; q < 4; ++q) rb[q] = *(const u32x4*)(bg + (size_t)q * 32 * ldb + k0);
;     }
; #pragma unroll
;     for (int kk = 0; kk < 2; ++kk) {
;       const int ch = ((kk * 4 + fq) ^ sw) << 4;
;       bf16x8 bfr[4], af[8];
; #pragma unroll
;       for (int n = 0; n < 4; ++n) bfr[n] = *(const bf16x8*)(smem + brow + n * 2048 + ch);
; #pragma unroll
;       for (int m = 0; m < 8; ++m) af[m] = *(const bf16x8*)(smem + arow + m * 2048 + ch);
.LBB0_128:
	s_cmp_gt_u32 s5, 30
	s_setprio 0
	s_barrier
	s_waitcnt vmcnt(0)
	ds_write_b128 v182, v[128:131]
	ds_write_b128 v182, v[132:135] offset:4096
	ds_write_b128 v182, v[148:151] offset:8192
	ds_write_b128 v182, v[136:139] offset:12288
	ds_write_b128 v182, v[152:155] offset:16384
	ds_write_b128 v182, v[144:147] offset:20480
	ds_write_b128 v182, v[156:159] offset:24576
	ds_write_b128 v182, v[140:143] offset:28672
	ds_write_b128 v182, v[172:175] offset:32768
	ds_write_b128 v182, v[168:171] offset:36864
	ds_write_b128 v182, v[164:167] offset:40960
	ds_write_b128 v182, v[160:163] offset:45056
	s_waitcnt lgkmcnt(0)
	s_barrier
	v_add_u32_e32 v185, v180, v183
	ds_read_b128 v[186:189], v185 offset:32768
	ds_read_b128 v[190:193], v185 offset:34816
	ds_read_b128 v[194:197], v185 offset:36864
	ds_read_b128 v[198:201], v185 offset:38912
	v_add_u32_e32 v185, v181, v183
	ds_read_b128 v[202:205], v185
	ds_read_b128 v[206:209], v185 offset:2048
	ds_read_b128 v[210:213], v185 offset:4096
	ds_read_b128 v[224:227], v185 offset:6144
	ds_read_b128 v[236:239], v185 offset:8192
	ds_read_b128 v[240:243], v185 offset:10240
	ds_read_b128 v[244:247], v185 offset:12288
	ds_read_b128 v[248:251], v185 offset:14336
	s_cbranch_scc1 .LBB0_127
	v_lshl_add_u64 v[140:141], v[176:177], 0, s[10:11]
	v_add_co_u32_e32 v128, vcc, 0x4c00000, v140
	v_lshl_add_u64 v[160:161], v[178:179], 0, s[10:11]
	s_nop 0
	v_addc_co_u32_e32 v129, vcc, 0, v141, vcc
	v_add_co_u32_e32 v132, vcc, 0x4c20000, v140
	s_nop 1
	v_addc_co_u32_e32 v133, vcc, 0, v141, vcc
	v_add_co_u32_e32 v136, vcc, 0x4c40000, v140
	global_load_dwordx4 v[128:131], v[128:129], off offset:128
	s_nop 0
	global_load_dwordx4 v[132:135], v[132:133], off offset:128
	v_addc_co_u32_e32 v137, vcc, 0, v141, vcc
	v_add_co_u32_e32 v138, vcc, 0x4c60000, v140
	s_nop 1
	v_addc_co_u32_e32 v139, vcc, 0, v141, vcc
	v_add_co_u32_e32 v142, vcc, 0x4c80000, v140
	global_load_dwordx4 v[148:151], v[136:137], off offset:128
	s_nop 0
	global_load_dwordx4 v[136:139], v[138:139], off offset:128
	v_addc_co_u32_e32 v143, vcc, 0, v141, vcc
	v_add_co_u32_e32 v144, vcc, 0x4ca0000, v140
	s_nop 1
	v_addc_co_u32_e32 v145, vcc, 0, v141, vcc
	global_load_dwordx4 v[152:155], v[142:143], off offset:128
	s_nop 0
	global_load_dwordx4 v[144:147], v[144:145], off offset:128
	v_add_co_u32_e32 v142, vcc, 0x4cc0000, v140
	s_nop 1
	v_addc_co_u32_e32 v143, vcc, 0, v141, vcc
	v_add_co_u32_e32 v140, vcc, 0x4ce0000, v140
	s_nop 1
	v_addc_co_u32_e32 v141, vcc, 0, v141, vcc
	v_add_co_u32_e32 v162, vcc, 0x400000, v160
	global_load_dwordx4 v[156:159], v[142:143], off offset:128
	s_nop 0
	global_load_dwordx4 v[140:143], v[140:141], off offset:128
	v_addc_co_u32_e32 v163, vcc, 0, v161, vcc
	v_add_co_u32_e32 v164, vcc, 0x420000, v160
	s_nop 1
	v_addc_co_u32_e32 v165, vcc, 0, v161, vcc
	global_load_dwordx4 v[172:175], v[162:163], off offset:128
	global_load_dwordx4 v[168:171], v[164:165], off offset:128
	v_add_co_u32_e32 v162, vcc, 0x440000, v160
	s_nop 1
	v_addc_co_u32_e32 v163, vcc, 0, v161, vcc
	v_add_co_u32_e32 v160, vcc, 0x460000, v160
	s_nop 1
	v_addc_co_u32_e32 v161, vcc, 0, v161, vcc
	global_load_dwordx4 v[164:167], v[162:163], off offset:128
	s_nop 0
	global_load_dwordx4 v[160:163], v[160:161], off offset:128
	s_branch .LBB0_127

; #define MFMA8(a, b, c) __builtin_amdgcn_mfma_f32_16x16x32_fp8_fp8(a, b, c, 0, 0, 0)
; template <bool FP8>
; __device__ __forceinline__ void gemm_tile_256(const u16* __restrict__ A, int lda, const u16* __restrict__ Bt, int ldb,
;                                               int K, char* smem, f32x4 (&acc)[8][4]) {
;     ...
; #pragma unroll
;     for (int kk = 0; kk < 2; ++kk) {
;       const int ch = ((kk * 4 + fq) ^ sw) << 4;
;       bf16x8 bfr[4], af[8];
; #pragma unroll
;       for (int n = 0; n < 4; ++n) bfr[n] = *(const bf16x8*)(smem + brow + n * 2048 + ch);
; #pragma unroll
;       for (int m = 0; m < 8; ++m) af[m] = *(const bf16x8*)(smem + arow + m * 2048 + ch);
;       __builtin_amdgcn_sched_group_barrier(0x100, 12, 0);
;       __builtin_amdgcn_sched_group_barrier(0x008, 32, 0);
; #pragma unroll
;       for (int m = 0; m < 8; ++m)
; #pragma unroll
;         for (int n = 0; n < 4; ++n) {
;           if (FP8) {
;             union { bf16x8 v; long l[2]; } ua, ub;
;             ua.v = af[m]; ub.v = bfr[n];
;             acc[m][n] = MFMA8(ub.l[0], ua.l[0], acc[m][n]);
;             acc[m][n] = MFMA8(ub.l[1], ua.l[1], acc[m][n]);
.LBB0_133:
	s_setprio 2
	s_waitcnt lgkmcnt(7)
	v_mfma_f32_16x16x32_fp8_fp8 v[60:63], v[176:177], v[208:209], v[60:63]
	s_add_u32 s10, s10, 0x80
	s_addc_u32 s11, s11, 0
	s_cmpk_lg_i32 s10, 0x800
	v_mfma_f32_16x16x32_fp8_fp8 v[56:59], v[180:181], v[208:209], v[56:59]
	v_mfma_f32_16x16x32_fp8_fp8 v[52:55], v[184:185], v[208:209], v[52:55]
	v_mfma_f32_16x16x32_fp8_fp8 v[48:51], v[188:189], v[208:209], v[48:51]
	s_waitcnt lgkmcnt(6)
	v_mfma_f32_16x16x32_fp8_fp8 v[44:47], v[176:177], v[212:213], v[44:47]
	v_mfma_f32_16x16x32_fp8_fp8 v[40:43], v[180:181], v[212:213], v[40:43]
	v_mfma_f32_16x16x32_fp8_fp8 v[36:39], v[184:185], v[212:213], v[36:39]
	v_mfma_f32_16x16x32_fp8_fp8 v[32:35], v[188:189], v[212:213], v[32:35]
	s_waitcnt lgkmcnt(5)
	v_mfma_f32_16x16x32_fp8_fp8 v[28:31], v[176:177], v[240:241], v[28:31]
	v_mfma_f32_16x16x32_fp8_fp8 v[24:27], v[180:181], v[240:241], v[24:27]
	v_mfma_f32_16x16x32_fp8_fp8 v[20:23], v[184:185], v[240:241], v[20:23]
	v_mfma_f32_16x16x32_fp8_fp8 v[16:19], v[188:189], v[240:241], v[16:19]
	s_waitcnt lgkmcnt(4)
	v_mfma_f32_16x16x32_fp8_fp8 v[12:15], v[176:177], v[244:245], v[12:15]
	v_mfma_f32_16x16x32_fp8_fp8 v[8:11], v[180:181], v[244:245], v[8:11]
	v_mfma_f32_16x16x32_fp8_fp8 v[4:7], v[184:185], v[244:245], v[4:7]
	v_mfma_f32_16x16x32_fp8_fp8 v[0:3], v[188:189], v[244:245], v[0:3]
	s_waitcnt lgkmcnt(3)
	v_mfma_f32_16x16x32_fp8_fp8 v[120:123], v[180:181], v[192:193], v[120:123]
	s_waitcnt lgkmcnt(2)
	v_mfma_f32_16x16x32_fp8_fp8 v[104:107], v[180:181], v[196:197], v[104:107]
	s_waitcnt lgkmcnt(1)
	v_mfma_f32_16x16x32_fp8_fp8 v[88:91], v[180:181], v[200:201], v[88:91]
	s_waitcnt lgkmcnt(0)
	v_mfma_f32_16x16x32_fp8_fp8 v[72:75], v[180:181], v[204:205], v[72:75]
	v_add_u32_e32 v180, v236, v239
	v_mfma_f32_16x16x32_fp8_fp8 v[60:63], v[178:179], v[210:211], v[60:63]
	v_mfma_f32_16x16x32_fp8_fp8 v[56:59], v[182:183], v[210:211], v[56:59]
	v_mfma_f32_16x16x32_fp8_fp8 v[52:55], v[186:187], v[210:211], v[52:55]
	v_mfma_f32_16x16x32_fp8_fp8 v[48:51], v[190:191], v[210:211], v[48:51]
	ds_read_b128 v[208:211], v180 offset:6144
	v_mfma_f32_16x16x32_fp8_fp8 v[44:47], v[178:179], v[214:215], v[44:47]
	v_mfma_f32_16x16x32_fp8_fp8 v[40:43], v[182:183], v[214:215], v[40:43]
	v_mfma_f32_16x16x32_fp8_fp8 v[36:39], v[186:187], v[214:215], v[36:39]
	v_mfma_f32_16x16x32_fp8_fp8 v[32:35], v[190:191], v[214:215], v[32:35]
	ds_read_b128 v[212:215], v180 offset:4096
	v_mfma_f32_16x16x32_fp8_fp8 v[28:31], v[178:179], v[242:243], v[28:31]
	v_mfma_f32_16x16x32_fp8_fp8 v[24:27], v[182:183], v[242:243], v[24:27]
	v_mfma_f32_16x16x32_fp8_fp8 v[20:23], v[186:187], v[242:243], v[20:23]
	v_mfma_f32_16x16x32_fp8_fp8 v[16:19], v[190:191], v[242:243], v[16:19]
	ds_read_b128 v[240:243], v180
	v_mfma_f32_16x16x32_fp8_fp8 v[12:15], v[178:179], v[246:247], v[12:15]
	v_mfma_f32_16x16x32_fp8_fp8 v[8:11], v[182:183], v[246:247], v[8:11]
	v_mfma_f32_16x16x32_fp8_fp8 v[4:7], v[186:187], v[246:247], v[4:7]
	v_mfma_f32_16x16x32_fp8_fp8 v[0:3], v[190:191], v[246:247], v[0:3]
	ds_read_b128 v[244:247], v180 offset:2048
	v_mfma_f32_16x16x32_fp8_fp8 v[76:79], v[176:177], v[204:205], v[76:79]
	v_mfma_f32_16x16x32_fp8_fp8 v[68:71], v[184:185], v[204:205], v[68:71]
	v_mfma_f32_16x16x32_fp8_fp8 v[64:67], v[188:189], v[204:205], v[64:67]
	v_mfma_f32_16x16x32_fp8_fp8 v[76:79], v[178:179], v[206:207], v[76:79]
	v_mfma_f32_16x16x32_fp8_fp8 v[72:75], v[182:183], v[206:207], v[72:75]
	v_mfma_f32_16x16x32_fp8_fp8 v[68:71], v[186:187], v[206:207], v[68:71]
	v_mfma_f32_16x16x32_fp8_fp8 v[64:67], v[190:191], v[206:207], v[64:67]
	ds_read_b128 v[204:207], v180 offset:8192
	v_mfma_f32_16x16x32_fp8_fp8 v[92:95], v[176:177], v[200:201], v[92:95]
	v_mfma_f32_16x16x32_fp8_fp8 v[84:87], v[184:185], v[200:201], v[84:87]
	v_mfma_f32_16x16x32_fp8_fp8 v[80:83], v[188:189], v[200:201], v[80:83]
	v_mfma_f32_16x16x32_fp8_fp8 v[92:95], v[178:179], v[202:203], v[92:95]
	v_mfma_f32_16x16x32_fp8_fp8 v[88:91], v[182:183], v[202:203], v[88:91]
	v_mfma_f32_16x16x32_fp8_fp8 v[84:87], v[186:187], v[202:203], v[84:87]
	v_mfma_f32_16x16x32_fp8_fp8 v[80:83], v[190:191], v[202:203], v[80:83]
	ds_read_b128 v[200:203], v180 offset:10240
	v_mfma_f32_16x16x32_fp8_fp8 v[108:111], v[176:177], v[196:197], v[108:111]
	v_mfma_f32_16x16x32_fp8_fp8 v[100:103], v[184:185], v[196:197], v[100:103]
	v_mfma_f32_16x16x32_fp8_fp8 v[96:99], v[188:189], v[196:197], v[96:99]
	v_mfma_f32_16x16x32_fp8_fp8 v[108:111], v[178:179], v[198:199], v[108:111]
	v_mfma_f32_16x16x32_fp8_fp8 v[104:107], v[182:183], v[198:199], v[104:107]
	v_mfma_f32_16x16x32_fp8_fp8 v[100:103], v[186:187], v[198:199], v[100:103]
	v_mfma_f32_16x16x32_fp8_fp8 v[96:99], v[190:191], v[198:199], v[96:99]
	ds_read_b128 v[196:199], v180 offset:12288
	v_mfma_f32_16x16x32_fp8_fp8 v[120:123], v[182:183], v[194:195], v[120:123]
	ds_read_b128 v[180:183], v180 offset:14336
	v_mfma_f32_16x16x32_fp8_fp8 v[112:115], v[188:189], v[192:193], v[112:115]
	v_mfma_f32_16x16x32_fp8_fp8 v[124:127], v[176:177], v[192:193], v[124:127]
	v_add_u32_e32 v176, v237, v239
	v_mfma_f32_16x16x32_fp8_fp8 v[112:115], v[190:191], v[194:195], v[112:115]
	ds_read_b128 v[188:191], v176 offset:34816
	v_mfma_f32_16x16x32_fp8_fp8 v[116:119], v[184:185], v[192:193], v[116:119]
	v_mfma_f32_16x16x32_fp8_fp8 v[116:119], v[186:187], v[194:195], v[116:119]
	ds_read_b128 v[184:187], v176 offset:36864
	v_mfma_f32_16x16x32_fp8_fp8 v[124:127], v[178:179], v[194:195], v[124:127]
	ds_read_b128 v[192:195], v176 offset:32768
	ds_read_b128 v[176:179], v176 offset:38912
	s_waitcnt lgkmcnt(1)
; #define MFMA8(a, b, c) __builtin_amdgcn_mfma_f32_16x16x32_fp8_fp8(a, b, c, 0, 0, 0)
; template <bool FP8>
; __device__ __forceinline__ void gemm_tile_256(const u16* __restrict__ A, int lda, const u16* __restrict__ Bt, int ldb,
;                                               int K, char* smem, f32x4 (&acc)[8][4]) {
;     ...
;       for (int m = 0; m < 8; ++m)
; #pragma unroll
;         for (int n = 0; n < 4; ++n) {
;           if (FP8) {
;             union { bf16x8 v; long l[2]; } ua, ub;
;             ua.v = af[m]; ub.v = bfr[n];
;             acc[m][n] = MFMA8(ub.l[0], ua.l[0], acc[m][n]);
;             acc[m][n] = MFMA8(ub.l[1], ua.l[1], acc[m][n]);
	v_mfma_f32_16x16x32_fp8_fp8 v[124:127], v[192:193], v[240:241], v[124:127]
	v_mfma_f32_16x16x32_fp8_fp8 v[120:123], v[188:189], v[240:241], v[120:123]
	v_mfma_f32_16x16x32_fp8_fp8 v[116:119], v[184:185], v[240:241], v[116:119]
	s_waitcnt lgkmcnt(0)
	v_mfma_f32_16x16x32_fp8_fp8 v[112:115], v[176:177], v[240:241], v[112:115]
	v_mfma_f32_16x16x32_fp8_fp8 v[108:111], v[192:193], v[244:245], v[108:111]
	v_mfma_f32_16x16x32_fp8_fp8 v[104:107], v[188:189], v[244:245], v[104:107]
	v_mfma_f32_16x16x32_fp8_fp8 v[100:103], v[184:185], v[244:245], v[100:103]
	v_mfma_f32_16x16x32_fp8_fp8 v[96:99], v[176:177], v[244:245], v[96:99]
	v_mfma_f32_16x16x32_fp8_fp8 v[92:95], v[192:193], v[212:213], v[92:95]
	v_mfma_f32_16x16x32_fp8_fp8 v[88:91], v[188:189], v[212:213], v[88:91]
	v_mfma_f32_16x16x32_fp8_fp8 v[84:87], v[184:185], v[212:213], v[84:87]
	v_mfma_f32_16x16x32_fp8_fp8 v[80:83], v[176:177], v[212:213], v[80:83]
	v_mfma_f32_16x16x32_fp8_fp8 v[76:79], v[192:193], v[208:209], v[76:79]
	v_mfma_f32_16x16x32_fp8_fp8 v[72:75], v[188:189], v[208:209], v[72:75]
	v_mfma_f32_16x16x32_fp8_fp8 v[68:71], v[184:185], v[208:209], v[68:71]
	v_mfma_f32_16x16x32_fp8_fp8 v[64:67], v[176:177], v[208:209], v[64:67]
	v_mfma_f32_16x16x32_fp8_fp8 v[60:63], v[192:193], v[204:205], v[60:63]
	v_mfma_f32_16x16x32_fp8_fp8 v[56:59], v[188:189], v[204:205], v[56:59]
	v_mfma_f32_16x16x32_fp8_fp8 v[52:55], v[184:185], v[204:205], v[52:55]
	v_mfma_f32_16x16x32_fp8_fp8 v[48:51], v[176:177], v[204:205], v[48:51]
	v_mfma_f32_16x16x32_fp8_fp8 v[44:47], v[192:193], v[200:201], v[44:47]
	v_mfma_f32_16x16x32_fp8_fp8 v[40:43], v[188:189], v[200:201], v[40:43]
	v_mfma_f32_16x16x32_fp8_fp8 v[36:39], v[184:185], v[200:201], v[36:39]
	v_mfma_f32_16x16x32_fp8_fp8 v[32:35], v[176:177], v[200:201], v[32:35]
	v_mfma_f32_16x16x32_fp8_fp8 v[28:31], v[192:193], v[196:197], v[28:31]
	v_mfma_f32_16x16x32_fp8_fp8 v[24:27], v[188:189], v[196:197], v[24:27]
	v_mfma_f32_16x16x32_fp8_fp8 v[20:23], v[184:185], v[196:197], v[20:23]
	v_mfma_f32_16x16x32_fp8_fp8 v[16:19], v[176:177], v[196:197], v[16:19]
	v_mfma_f32_16x16x32_fp8_fp8 v[12:15], v[192:193], v[180:181], v[12:15]
	v_mfma_f32_16x16x32_fp8_fp8 v[8:11], v[188:189], v[180:181], v[8:11]
	v_mfma_f32_16x16x32_fp8_fp8 v[4:7], v[184:185], v[180:181], v[4:7]
	v_mfma_f32_16x16x32_fp8_fp8 v[0:3], v[176:177], v[180:181], v[0:3]
	v_mfma_f32_16x16x32_fp8_fp8 v[124:127], v[194:195], v[242:243], v[124:127]
	v_mfma_f32_16x16x32_fp8_fp8 v[120:123], v[190:191], v[242:243], v[120:123]
	v_mfma_f32_16x16x32_fp8_fp8 v[116:119], v[186:187], v[242:243], v[116:119]
	v_mfma_f32_16x16x32_fp8_fp8 v[112:115], v[178:179], v[242:243], v[112:115]
	v_mfma_f32_16x16x32_fp8_fp8 v[108:111], v[194:195], v[246:247], v[108:111]
	v_mfma_f32_16x16x32_fp8_fp8 v[104:107], v[190:191], v[246:247], v[104:107]
	v_mfma_f32_16x16x32_fp8_fp8 v[100:103], v[186:187], v[246:247], v[100:103]
	v_mfma_f32_16x16x32_fp8_fp8 v[96:99], v[178:179], v[246:247], v[96:99]
	v_mfma_f32_16x16x32_fp8_fp8 v[92:95], v[194:195], v[214:215], v[92:95]
	v_mfma_f32_16x16x32_fp8_fp8 v[88:91], v[190:191], v[214:215], v[88:91]
	v_mfma_f32_16x16x32_fp8_fp8 v[84:87], v[186:187], v[214:215], v[84:87]
	v_mfma_f32_16x16x32_fp8_fp8 v[80:83], v[178:179], v[214:215], v[80:83]
	v_mfma_f32_16x16x32_fp8_fp8 v[76:79], v[194:195], v[210:211], v[76:79]
	v_mfma_f32_16x16x32_fp8_fp8 v[72:75], v[190:191], v[210:211], v[72:75]
	v_mfma_f32_16x16x32_fp8_fp8 v[68:71], v[186:187], v[210:211], v[68:71]
	v_mfma_f32_16x16x32_fp8_fp8 v[64:67], v[178:179], v[210:211], v[64:67]
	v_mfma_f32_16x16x32_fp8_fp8 v[60:63], v[194:195], v[206:207], v[60:63]
	v_mfma_f32_16x16x32_fp8_fp8 v[56:59], v[190:191], v[206:207], v[56:59]
	v_mfma_f32_16x16x32_fp8_fp8 v[52:55], v[186:187], v[206:207], v[52:55]
	v_mfma_f32_16x16x32_fp8_fp8 v[48:51], v[178:179], v[206:207], v[48:51]
	v_mfma_f32_16x16x32_fp8_fp8 v[44:47], v[194:195], v[202:203], v[44:47]
	v_mfma_f32_16x16x32_fp8_fp8 v[40:43], v[190:191], v[202:203], v[40:43]
	v_mfma_f32_16x16x32_fp8_fp8 v[36:39], v[186:187], v[202:203], v[36:39]
	v_mfma_f32_16x16x32_fp8_fp8 v[32:35], v[178:179], v[202:203], v[32:35]
	v_mfma_f32_16x16x32_fp8_fp8 v[28:31], v[194:195], v[198:199], v[28:31]
	v_mfma_f32_16x16x32_fp8_fp8 v[24:27], v[190:191], v[198:199], v[24:27]
	v_mfma_f32_16x16x32_fp8_fp8 v[20:23], v[186:187], v[198:199], v[20:23]
	v_mfma_f32_16x16x32_fp8_fp8 v[16:19], v[178:179], v[198:199], v[16:19]
	v_mfma_f32_16x16x32_fp8_fp8 v[12:15], v[194:195], v[182:183], v[12:15]
	v_mfma_f32_16x16x32_fp8_fp8 v[8:11], v[190:191], v[182:183], v[8:11]
	v_mfma_f32_16x16x32_fp8_fp8 v[4:7], v[186:187], v[182:183], v[4:7]
	v_mfma_f32_16x16x32_fp8_fp8 v[0:3], v[178:179], v[182:183], v[0:3]
	s_cbranch_scc0 .LBB0_136
; template <bool FP8>
; __device__ __forceinline__ void gemm_tile_256(const u16* __restrict__ A, int lda, const u16* __restrict__ Bt, int ldb,
;                                               int K, char* smem, f32x4 (&acc)[8][4]) {
;     ...
;   for (int kt = 0; kt < nk; ++kt) {
;     __syncthreads();
; #pragma unroll
;     for (int q = 0; q < 8; ++q) *(u32x4*)(smem + wofs + q * 4096) = ra[q];
; #pragma unroll
;     for (int q = 0; q < 4; ++q) *(u32x4*)(smem + 32768 + wofs + q * 4096) = rb[q];
;     __syncthreads();
;     if (kt + 1 < nk) {
;       const int k0 = (kt + 1) << 6;
; #pragma unroll
;       for (int q = 0; q < 8; ++q) ra[q] = *(const u32x4*)(ag + (size_t)q * 32 * lda + k0);
; #pragma unroll
;       for (int q = 0; q < 4; ++q) rb[q] = *(const u32x4*)(bg + (size_t)q * 32 * ldb + k0);
;     }
; #pragma unroll
;     for (int kk = 0; kk < 2; ++kk) {
;       const int ch = ((kk * 4 + fq) ^ sw) << 4;
;       bf16x8 bfr[4], af[8];
; #pragma unroll
;       for (int n = 0; n < 4; ++n) bfr[n] = *(const bf16x8*)(smem + brow + n * 2048 + ch);
; #pragma unroll
;       for (int m = 0; m < 8; ++m) af[m] = *(const bf16x8*)(smem + arow + m * 2048 + ch);
.LBB0_134:
	s_cmpk_eq_i32 s10, 0x780
	s_setprio 0
	s_barrier
	s_waitcnt vmcnt(11)
	ds_write_b128 v235, v[128:131]
	s_waitcnt vmcnt(10)
	ds_write_b128 v235, v[132:135] offset:4096
	s_waitcnt vmcnt(9)
	ds_write_b128 v235, v[136:139] offset:8192
	s_waitcnt vmcnt(8)
	ds_write_b128 v235, v[140:143] offset:12288
	s_waitcnt vmcnt(7)
	ds_write_b128 v235, v[144:147] offset:16384
	s_waitcnt vmcnt(6)
	ds_write_b128 v235, v[148:151] offset:20480
	s_waitcnt vmcnt(5)
	ds_write_b128 v235, v[152:155] offset:24576
	s_waitcnt vmcnt(4)
	ds_write_b128 v235, v[156:159] offset:28672
	s_waitcnt vmcnt(3)
	ds_write_b128 v235, v[160:163] offset:32768
	s_waitcnt vmcnt(2)
	ds_write_b128 v235, v[164:167] offset:36864
	s_waitcnt vmcnt(1)
	ds_write_b128 v235, v[168:171] offset:40960
	s_waitcnt vmcnt(0)
	ds_write_b128 v235, v[172:175] offset:45056
	s_waitcnt lgkmcnt(0)
	s_barrier
	v_add_u32_e32 v188, v237, v238
	ds_read_b128 v[176:179], v188 offset:32768
	ds_read_b128 v[180:183], v188 offset:34816
	ds_read_b128 v[184:187], v188 offset:36864
	ds_read_b128 v[188:191], v188 offset:38912
	v_add_u32_e32 v220, v236, v238
	ds_read_b128 v[208:211], v220 offset:8192
	ds_read_b128 v[212:215], v220 offset:10240
	ds_read_b128 v[240:243], v220 offset:12288
	ds_read_b128 v[244:247], v220 offset:14336
	ds_read_b128 v[192:195], v220
	ds_read_b128 v[196:199], v220 offset:2048
	ds_read_b128 v[200:203], v220 offset:4096
	ds_read_b128 v[204:207], v220 offset:6144
	s_cbranch_scc1 .LBB0_133
	v_lshl_add_u64 v[152:153], v[224:225], 0, s[10:11]
	v_add_co_u32_e32 v128, vcc, 0x38c00000, v152
	v_lshl_add_u64 v[168:169], v[226:227], 0, s[10:11]
	s_nop 0
	v_addc_co_u32_e32 v129, vcc, 0, v153, vcc
	v_add_co_u32_e32 v132, vcc, 0x38c10000, v152
	s_nop 1
	v_addc_co_u32_e32 v133, vcc, 0, v153, vcc
	v_add_co_u32_e32 v136, vcc, 0x38c20000, v152
	global_load_dwordx4 v[128:131], v[128:129], off offset:128
	s_nop 0
	global_load_dwordx4 v[132:135], v[132:133], off offset:128
	v_addc_co_u32_e32 v137, vcc, 0, v153, vcc
	v_add_co_u32_e32 v140, vcc, 0x38c30000, v152
	s_nop 1
	v_addc_co_u32_e32 v141, vcc, 0, v153, vcc
	v_add_co_u32_e32 v144, vcc, 0x38c40000, v152
	global_load_dwordx4 v[136:139], v[136:137], off offset:128
	s_nop 0
	global_load_dwordx4 v[140:143], v[140:141], off offset:128
	v_addc_co_u32_e32 v145, vcc, 0, v153, vcc
	v_add_co_u32_e32 v148, vcc, 0x38c50000, v152
	s_nop 1
	v_addc_co_u32_e32 v149, vcc, 0, v153, vcc
	v_add_co_u32_e32 v154, vcc, 0x38c60000, v152
	global_load_dwordx4 v[144:147], v[144:145], off offset:128
	s_nop 0
	global_load_dwordx4 v[148:151], v[148:149], off offset:128
	v_addc_co_u32_e32 v155, vcc, 0, v153, vcc
	v_add_co_u32_e32 v156, vcc, 0x38c70000, v152
	s_nop 1
	v_addc_co_u32_e32 v157, vcc, 0, v153, vcc
	v_add_co_u32_e32 v160, vcc, 0x3cc00000, v168
	global_load_dwordx4 v[152:155], v[154:155], off offset:128
	s_nop 0
	global_load_dwordx4 v[156:159], v[156:157], off offset:128
	v_addc_co_u32_e32 v161, vcc, 0, v169, vcc
	v_add_co_u32_e32 v164, vcc, 0x3cc10000, v168
	s_nop 1
	v_addc_co_u32_e32 v165, vcc, 0, v169, vcc
	v_add_co_u32_e32 v170, vcc, 0x3cc20000, v168
	global_load_dwordx4 v[160:163], v[160:161], off offset:128
	s_nop 0
	global_load_dwordx4 v[164:167], v[164:165], off offset:128
	v_addc_co_u32_e32 v171, vcc, 0, v169, vcc
	v_add_co_u32_e32 v172, vcc, 0x3cc30000, v168
	s_nop 1
	v_addc_co_u32_e32 v173, vcc, 0, v169, vcc
	global_load_dwordx4 v[168:171], v[170:171], off offset:128
	s_nop 0
	global_load_dwordx4 v[172:175], v[172:173], off offset:128
	s_branch .LBB0_133

; __device__ __forceinline__ float lo_bf(unsigned u) { return __uint_as_float(u << 16); }
; __device__ __forceinline__ float hi_bf(unsigned u) { return __uint_as_float(u & 0xffff0000u); }
; __device__ __forceinline__ void conv32(const u16* __restrict__ src  , const float* cwl  ,
;                                        int row, int tglob, int col, int cl  , float (&y)[32]) {
; #pragma unroll
;   for (int sb = 0; sb < 4; ++sb) {
;     float acc[8];
; #pragma unroll
;     for (int j = 0; j < 8; ++j) acc[j] = 0.f;
; #pragma unroll
;     for (int i = 0; i < 4; ++i) {
;       const int dt = i - 3;
;       if (tglob + dt >= 0) {
;         uint4 xv = *(const uint4*)(src + (size_t)(row + dt) * 3072 + col + sb * 8);
;         float4 w0 = *(const float4*)(cwl + i * 128 + cl + sb * 8);
;         float4 w1 = *(const float4*)(cwl + i * 128 + cl + sb * 8 + 4);
;         acc[0] += w0.x * lo_bf(xv.x); acc[1] += w0.y * hi_bf(xv.x);
;         acc[2] += w0.z * lo_bf(xv.y); acc[3] += w0.w * hi_bf(xv.y);
;         acc[4] += w1.x * lo_bf(xv.z); acc[5] += w1.y * hi_bf(xv.z);
;         acc[6] += w1.z * lo_bf(xv.w); acc[7] += w1.w * hi_bf(xv.w);
;       }
;     }
.LBB0_699:
	s_or_b64 exec, exec, s[8:9]
	s_waitcnt lgkmcnt(0)
	s_barrier
	ds_read2st64_b32 v[84:85], v92 offset1:2
	v_or_b32_e32 v0, s19, v93
	v_lshlrev_b32_e32 v0, 1, v0
	v_mov_b32_e32 v6, v1
	v_mov_b32_e32 v7, v1
	v_add_u32_e32 v168, s91, v88
	v_add_u32_e32 v16, s90, v88
	v_lshl_add_u64 v[86:87], s[34:35], 0, v[0:1]
	v_cmp_lt_i32_e64 s[98:99], 2, v16
	v_add_u32_e32 v250, -3, v168
	s_and_saveexec_b64 s[100:101], s[98:99]
	v_mad_i64_i32 v[250:251], s[98:99], v250, s63, v[86:87]
	global_load_dwordx4 v[196:199], v[250:251], off
	global_load_dwordx4 v[212:215], v[250:251], off offset:16
	global_load_dwordx4 v[234:237], v[250:251], off offset:32
	s_or_b64 exec, exec, s[100:101]
	v_cmp_lt_i32_e64 s[98:99], 1, v16
	v_add_u32_e32 v250, -2, v168
	s_and_saveexec_b64 s[100:101], s[98:99]
	v_mad_i64_i32 v[250:251], s[98:99], v250, s63, v[86:87]
	global_load_dwordx4 v[200:203], v[250:251], off
	global_load_dwordx4 v[220:223], v[250:251], off offset:16
	global_load_dwordx4 v[238:241], v[250:251], off offset:32
	s_or_b64 exec, exec, s[100:101]
	v_cmp_lt_i32_e64 s[98:99], 0, v16
	v_add_u32_e32 v250, -1, v168
	s_and_saveexec_b64 s[100:101], s[98:99]
	v_mad_i64_i32 v[250:251], s[98:99], v250, s63, v[86:87]
	global_load_dwordx4 v[204:207], v[250:251], off
	global_load_dwordx4 v[224:227], v[250:251], off offset:16
	global_load_dwordx4 v[242:245], v[250:251], off offset:32
	s_or_b64 exec, exec, s[100:101]
	v_cmp_lt_i32_e64 s[98:99], -1, v16
	v_add_u32_e32 v250, 0, v168
	s_and_saveexec_b64 s[100:101], s[98:99]
	v_mad_i64_i32 v[250:251], s[98:99], v250, s63, v[86:87]
	global_load_dwordx4 v[208:211], v[250:251], off
	global_load_dwordx4 v[230:233], v[250:251], off offset:16
	global_load_dwordx4 v[246:249], v[250:251], off offset:32
	s_or_b64 exec, exec, s[100:101]
	s_waitcnt vmcnt(0)
	v_mov_b32_e32 v0, v1
	v_mov_b32_e32 v2, v1
	v_mov_b32_e32 v3, v1
	v_mov_b32_e32 v4, v1
	v_mov_b32_e32 v5, v1
	v_mov_b64_e32 v[14:15], v[6:7]
	v_cmp_lt_i32_e32 vcc, 2, v16
	v_add_u32_e32 v169, -3, v168
	v_mov_b64_e32 v[12:13], v[4:5]
	v_mov_b64_e32 v[10:11], v[2:3]
	v_mov_b64_e32 v[8:9], v[0:1]
	s_and_saveexec_b64 s[8:9], vcc
	s_cbranch_execz .LBB0_701
	v_mov_b64_e32 v[2:3], v[196:197]
	v_mov_b64_e32 v[4:5], v[198:199]
	ds_read_b128 v[6:9], v94 offset:53248
	ds_read_b128 v[10:13], v94 offset:53264
	s_waitcnt vmcnt(0)
	v_lshlrev_b32_e32 v18, 16, v2
	v_and_b32_e32 v19, 0xffff0000, v2
	v_lshlrev_b32_e32 v2, 16, v3
	v_and_b32_e32 v3, 0xffff0000, v3
	v_lshlrev_b32_e32 v20, 16, v4
	v_and_b32_e32 v21, 0xffff0000, v4
	v_lshlrev_b32_e32 v4, 16, v5
	v_and_b32_e32 v5, 0xffff0000, v5
	s_waitcnt lgkmcnt(0)
	v_pk_fma_f32 v[14:15], v[12:13], v[4:5], 0 op_sel_hi:[1,1,0]
	v_pk_fma_f32 v[12:13], v[10:11], v[20:21], 0 op_sel_hi:[1,1,0]
	v_pk_fma_f32 v[10:11], v[8:9], v[2:3], 0 op_sel_hi:[1,1,0]
	v_pk_fma_f32 v[8:9], v[6:7], v[18:19], 0 op_sel_hi:[1,1,0]
.LBB0_701:
	s_or_b64 exec, exec, s[8:9]
	v_cmp_lt_i32_e64 s[90:91], 1, v16
	v_add_u32_e32 v170, -2, v168
	s_and_saveexec_b64 s[8:9], s[90:91]
	s_cbranch_execz .LBB0_703
	v_mov_b64_e32 v[2:3], v[200:201]
	v_mov_b64_e32 v[4:5], v[202:203]
	ds_read_b128 v[18:21], v94 offset:53760
	ds_read_b128 v[22:25], v94 offset:53776
	s_waitcnt vmcnt(0)
	v_lshlrev_b32_e32 v6, 16, v2
	v_and_b32_e32 v7, 0xffff0000, v2
	v_lshlrev_b32_e32 v2, 16, v3
	v_and_b32_e32 v3, 0xffff0000, v3
	v_lshlrev_b32_e32 v26, 16, v4
	v_and_b32_e32 v27, 0xffff0000, v4
	v_lshlrev_b32_e32 v4, 16, v5
	v_and_b32_e32 v5, 0xffff0000, v5
	s_waitcnt lgkmcnt(0)
	v_pk_fma_f32 v[14:15], v[24:25], v[4:5], v[14:15]
	v_pk_fma_f32 v[12:13], v[22:23], v[26:27], v[12:13]
	v_pk_fma_f32 v[10:11], v[20:21], v[2:3], v[10:11]
	v_pk_fma_f32 v[8:9], v[18:19], v[6:7], v[8:9]
.LBB0_703:
	s_or_b64 exec, exec, s[8:9]
	v_cmp_lt_i32_e64 s[92:93], 0, v16
	v_add_u32_e32 v171, -1, v168
	s_and_saveexec_b64 s[8:9], s[92:93]
	s_cbranch_execz .LBB0_705
	v_mov_b64_e32 v[2:3], v[204:205]
	v_mov_b64_e32 v[4:5], v[206:207]
	ds_read_b128 v[18:21], v94 offset:54272
	ds_read_b128 v[22:25], v94 offset:54288
	s_waitcnt vmcnt(0)
	v_lshlrev_b32_e32 v6, 16, v2
	v_and_b32_e32 v7, 0xffff0000, v2
	v_lshlrev_b32_e32 v2, 16, v3
	v_and_b32_e32 v3, 0xffff0000, v3
	v_lshlrev_b32_e32 v26, 16, v4
	v_and_b32_e32 v27, 0xffff0000, v4
	v_lshlrev_b32_e32 v4, 16, v5
	v_and_b32_e32 v5, 0xffff0000, v5
	s_waitcnt lgkmcnt(0)
	v_pk_fma_f32 v[14:15], v[24:25], v[4:5], v[14:15]
	v_pk_fma_f32 v[12:13], v[22:23], v[26:27], v[12:13]
	v_pk_fma_f32 v[10:11], v[20:21], v[2:3], v[10:11]
	v_pk_fma_f32 v[8:9], v[18:19], v[6:7], v[8:9]
.LBB0_705:
	s_or_b64 exec, exec, s[8:9]
	v_cmp_lt_i32_e64 s[94:95], -1, v16
	s_and_saveexec_b64 s[8:9], s[94:95]
	s_cbranch_execz .LBB0_707
	v_mov_b64_e32 v[2:3], v[208:209]
	v_mov_b64_e32 v[4:5], v[210:211]
	ds_read_b128 v[16:19], v94 offset:54784
	ds_read_b128 v[20:23], v94 offset:54800
	s_waitcnt vmcnt(0)
	v_lshlrev_b32_e32 v6, 16, v2
	v_and_b32_e32 v7, 0xffff0000, v2
	v_lshlrev_b32_e32 v2, 16, v3
	v_and_b32_e32 v3, 0xffff0000, v3
	v_lshlrev_b32_e32 v24, 16, v4
	v_and_b32_e32 v25, 0xffff0000, v4
	v_lshlrev_b32_e32 v4, 16, v5
	v_and_b32_e32 v5, 0xffff0000, v5
	s_waitcnt lgkmcnt(0)
	v_pk_fma_f32 v[14:15], v[22:23], v[4:5], v[14:15]
	v_pk_fma_f32 v[12:13], v[20:21], v[24:25], v[12:13]
	v_pk_fma_f32 v[10:11], v[18:19], v[2:3], v[10:11]
	v_pk_fma_f32 v[8:9], v[16:17], v[6:7], v[8:9]

; __device__ __forceinline__ float lo_bf(unsigned u) { return __uint_as_float(u << 16); }
; __device__ __forceinline__ float hi_bf(unsigned u) { return __uint_as_float(u & 0xffff0000u); }
; __device__ __forceinline__ void conv32(const u16* __restrict__ src  , const float* cwl  ,
;                                        int row, int tglob, int col, int cl  , float (&y)[32]) {
;     ...
;     for (int i = 0; i < 4; ++i) {
;       const int dt = i - 3;
;       if (tglob + dt >= 0) {
;         uint4 xv = *(const uint4*)(src + (size_t)(row + dt) * 3072 + col + sb * 8);
;         float4 w0 = *(const float4*)(cwl + i * 128 + cl + sb * 8);
;         float4 w1 = *(const float4*)(cwl + i * 128 + cl + sb * 8 + 4);
;         acc[0] += w0.x * lo_bf(xv.x); acc[1] += w0.y * hi_bf(xv.x);
;         acc[2] += w0.z * lo_bf(xv.y); acc[3] += w0.w * hi_bf(xv.y);
;         acc[4] += w1.x * lo_bf(xv.z); acc[5] += w1.y * hi_bf(xv.z);
;         acc[6] += w1.z * lo_bf(xv.w); acc[7] += w1.w * hi_bf(xv.w);
;       }
.LBB0_711:
	v_mov_b64_e32 v[2:3], v[230:231]
	v_mov_b64_e32 v[4:5], v[232:233]
	ds_read_b128 v[24:27], v94 offset:54816
	ds_read_b128 v[28:31], v94 offset:54832
	s_waitcnt vmcnt(0)
	v_lshlrev_b32_e32 v6, 16, v2
	v_and_b32_e32 v7, 0xffff0000, v2
	v_lshlrev_b32_e32 v2, 16, v3
	v_and_b32_e32 v3, 0xffff0000, v3
	v_lshlrev_b32_e32 v32, 16, v4
	v_and_b32_e32 v33, 0xffff0000, v4
	v_lshlrev_b32_e32 v4, 16, v5
	v_and_b32_e32 v5, 0xffff0000, v5
	s_waitcnt lgkmcnt(0)
	v_pk_fma_f32 v[22:23], v[30:31], v[4:5], v[22:23]
	v_pk_fma_f32 v[20:21], v[28:29], v[32:33], v[20:21]
	v_pk_fma_f32 v[18:19], v[26:27], v[2:3], v[18:19]
	v_pk_fma_f32 v[16:17], v[24:25], v[6:7], v[16:17]

; __device__ __forceinline__ float lo_bf(unsigned u) { return __uint_as_float(u << 16); }
; __device__ __forceinline__ float hi_bf(unsigned u) { return __uint_as_float(u & 0xffff0000u); }
; __device__ __forceinline__ void conv32(const u16* __restrict__ src  , const float* cwl  ,
;                                        int row, int tglob, int col, int cl  , float (&y)[32]) {
;     ...
;     for (int i = 0; i < 4; ++i) {
;       const int dt = i - 3;
;       if (tglob + dt >= 0) {
;         uint4 xv = *(const uint4*)(src + (size_t)(row + dt) * 3072 + col + sb * 8);
;         float4 w0 = *(const float4*)(cwl + i * 128 + cl + sb * 8);
;         float4 w1 = *(const float4*)(cwl + i * 128 + cl + sb * 8 + 4);
;         acc[0] += w0.x * lo_bf(xv.x); acc[1] += w0.y * hi_bf(xv.x);
;         acc[2] += w0.z * lo_bf(xv.y); acc[3] += w0.w * hi_bf(xv.y);
;         acc[4] += w1.x * lo_bf(xv.z); acc[5] += w1.y * hi_bf(xv.z);
;         acc[6] += w1.z * lo_bf(xv.w); acc[7] += w1.w * hi_bf(xv.w);
;       }
.LBB0_716:
	v_mov_b64_e32 v[2:3], v[246:247]
	v_mov_b64_e32 v[4:5], v[248:249]
	ds_read_b128 v[24:27], v94 offset:54848
	ds_read_b128 v[28:31], v94 offset:54864
	s_waitcnt vmcnt(0)
	v_lshlrev_b32_e32 v6, 16, v2
	v_and_b32_e32 v7, 0xffff0000, v2
	v_lshlrev_b32_e32 v2, 16, v3
	v_and_b32_e32 v3, 0xffff0000, v3
	v_lshlrev_b32_e32 v40, 16, v4
	v_and_b32_e32 v41, 0xffff0000, v4
	v_lshlrev_b32_e32 v4, 16, v5
	v_and_b32_e32 v5, 0xffff0000, v5
	s_waitcnt lgkmcnt(0)
	v_pk_fma_f32 v[38:39], v[30:31], v[4:5], v[38:39]
	v_pk_fma_f32 v[36:37], v[28:29], v[40:41], v[36:37]
	v_pk_fma_f32 v[34:35], v[26:27], v[2:3], v[34:35]
	v_pk_fma_f32 v[32:33], v[24:25], v[6:7], v[32:33]

; __device__ __forceinline__ float siluf_(float x) { return x * __builtin_amdgcn_rcpf(1.f + __expf(-x)); }
; __device__ __forceinline__ void conv32(const u16* __restrict__ src  , const float* cwl  ,
;                                        int row, int tglob, int col, int cl  , float (&y)[32]) {
;     ...
; #pragma unroll
;     for (int j = 0; j < 8; ++j) y[sb * 8 + j] = siluf_(acc[j]);
; __device__ __forceinline__ void phase_dnprep(const Params& p, char* smem) {
;     ...
;       float ss = 0.f;
; #pragma unroll
;       for (int j = 0; j < 32; ++j) ss += y[j] * y[j];
.LBB0_722:
	s_or_b64 exec, exec, s[8:9]
	v_mul_f32_e32 v0, 0xbfb8aa3b, v32
	v_exp_f32_e32 v0, v0
	s_mul_i32 s8, s4, 0xe000
	s_mul_hi_i32 s9, s4, 0xe000
	s_add_u32 s8, s52, s8
	v_add_f32_e32 v0, 1.0, v0
	v_rcp_f32_e32 v2, v0
	v_mul_f32_e32 v0, 0xbfb8aa3b, v33
	v_exp_f32_e32 v0, v0
	s_addc_u32 s9, s53, s9
	v_add_f32_e32 v0, 1.0, v0
	v_rcp_f32_e32 v3, v0
	v_mul_f32_e32 v0, 0xbfb8aa3b, v34
	v_exp_f32_e32 v0, v0
	v_pk_mul_f32 v[2:3], v[32:33], v[2:3]
	s_nop 0
	v_pk_mul_f32 v[188:189], v[2:3], v[2:3]
	v_add_f32_e32 v0, 1.0, v0
	v_rcp_f32_e32 v4, v0
	v_mul_f32_e32 v0, 0xbfb8aa3b, v35
	v_exp_f32_e32 v0, v0
	s_nop 0
	v_add_f32_e32 v0, 1.0, v0
	v_rcp_f32_e32 v5, v0
	v_mul_f32_e32 v0, 0xbfb8aa3b, v36
	v_exp_f32_e32 v0, v0
	v_pk_mul_f32 v[4:5], v[34:35], v[4:5]
	s_nop 0
	v_pk_mul_f32 v[190:191], v[4:5], v[4:5]
	v_add_f32_e32 v0, 1.0, v0
	v_rcp_f32_e32 v6, v0
	v_mul_f32_e32 v0, 0xbfb8aa3b, v37
	v_exp_f32_e32 v0, v0
	s_nop 0
	v_add_f32_e32 v0, 1.0, v0
	v_rcp_f32_e32 v7, v0
	v_mul_f32_e32 v0, 0xbfb8aa3b, v38
	v_exp_f32_e32 v0, v0
	v_pk_mul_f32 v[6:7], v[36:37], v[6:7]
	s_nop 0
	v_pk_mul_f32 v[192:193], v[6:7], v[6:7]
	v_add_f32_e32 v0, 1.0, v0
	v_rcp_f32_e32 v32, v0
	v_mul_f32_e32 v0, 0xbfb8aa3b, v39
	v_exp_f32_e32 v0, v0
	s_nop 0
	v_add_f32_e32 v0, 1.0, v0
	v_rcp_f32_e32 v33, v0
	v_mul_f32_e32 v0, 0xbfb8aa3b, v16
	v_exp_f32_e32 v0, v0
	v_pk_mul_f32 v[32:33], v[38:39], v[32:33]
	s_nop 0
	v_pk_mul_f32 v[194:195], v[32:33], v[32:33]
	v_add_f32_e32 v0, 1.0, v0
	v_rcp_f32_e32 v34, v0
	v_mul_f32_e32 v0, 0xbfb8aa3b, v17
	v_exp_f32_e32 v0, v0
	s_nop 0
	v_add_f32_e32 v0, 1.0, v0
	v_rcp_f32_e32 v35, v0
	v_mul_f32_e32 v0, 0xbfb8aa3b, v18
	v_exp_f32_e32 v0, v0
	v_pk_mul_f32 v[16:17], v[16:17], v[34:35]
	s_nop 0
	v_pk_mul_f32 v[180:181], v[16:17], v[16:17]
	v_add_f32_e32 v0, 1.0, v0
	v_rcp_f32_e32 v34, v0
	v_mul_f32_e32 v0, 0xbfb8aa3b, v19
	v_exp_f32_e32 v0, v0
	s_nop 0
	v_add_f32_e32 v0, 1.0, v0
	v_rcp_f32_e32 v35, v0
	v_mul_f32_e32 v0, 0xbfb8aa3b, v20
	v_exp_f32_e32 v0, v0
	v_pk_mul_f32 v[18:19], v[18:19], v[34:35]
	s_nop 0
	v_pk_mul_f32 v[182:183], v[18:19], v[18:19]
	v_add_f32_e32 v0, 1.0, v0
	v_rcp_f32_e32 v34, v0
	v_mul_f32_e32 v0, 0xbfb8aa3b, v21
	v_exp_f32_e32 v0, v0
	s_nop 0
	v_add_f32_e32 v0, 1.0, v0
	v_rcp_f32_e32 v35, v0
	v_mul_f32_e32 v0, 0xbfb8aa3b, v22
	v_exp_f32_e32 v0, v0
	v_pk_mul_f32 v[20:21], v[20:21], v[34:35]
	s_nop 0
	v_pk_mul_f32 v[184:185], v[20:21], v[20:21]
	v_add_f32_e32 v0, 1.0, v0
	v_rcp_f32_e32 v34, v0
	v_mul_f32_e32 v0, 0xbfb8aa3b, v23
	v_exp_f32_e32 v0, v0
	s_nop 0
	v_add_f32_e32 v0, 1.0, v0
	v_rcp_f32_e32 v35, v0
	v_mul_f32_e32 v0, 0xbfb8aa3b, v8
	v_exp_f32_e32 v0, v0
	v_pk_mul_f32 v[22:23], v[22:23], v[34:35]
	s_nop 0
	v_pk_mul_f32 v[186:187], v[22:23], v[22:23]
	v_add_f32_e32 v0, 1.0, v0
	v_rcp_f32_e32 v34, v0
	v_mul_f32_e32 v0, 0xbfb8aa3b, v9
	v_exp_f32_e32 v0, v0
	s_nop 0
	v_add_f32_e32 v0, 1.0, v0
	v_rcp_f32_e32 v35, v0
	v_mul_f32_e32 v0, 0xbfb8aa3b, v10
	v_exp_f32_e32 v0, v0
	v_pk_mul_f32 v[8:9], v[8:9], v[34:35]
	s_nop 0
	v_pk_mul_f32 v[172:173], v[8:9], v[8:9]
	v_add_f32_e32 v0, 1.0, v0
	v_rcp_f32_e32 v34, v0
	v_mul_f32_e32 v0, 0xbfb8aa3b, v11
	v_exp_f32_e32 v0, v0
	s_nop 0
	v_add_f32_e32 v0, 1.0, v0
	v_rcp_f32_e32 v35, v0
	v_mul_f32_e32 v0, 0xbfb8aa3b, v12
	v_exp_f32_e32 v0, v0
	v_pk_mul_f32 v[10:11], v[10:11], v[34:35]
	s_nop 0
	v_pk_mul_f32 v[174:175], v[10:11], v[10:11]
	v_add_f32_e32 v0, 1.0, v0
	v_rcp_f32_e32 v34, v0
	v_mul_f32_e32 v0, 0xbfb8aa3b, v13
	v_exp_f32_e32 v0, v0
	s_nop 0
	v_add_f32_e32 v0, 1.0, v0
	v_rcp_f32_e32 v35, v0
	v_mul_f32_e32 v0, 0xbfb8aa3b, v14
	v_exp_f32_e32 v0, v0
	v_pk_mul_f32 v[12:13], v[12:13], v[34:35]
	s_nop 0
	v_pk_mul_f32 v[176:177], v[12:13], v[12:13]
	v_add_f32_e32 v0, 1.0, v0
	v_rcp_f32_e32 v34, v0
	v_mul_f32_e32 v0, 0xbfb8aa3b, v15
	v_exp_f32_e32 v0, v0
	s_nop 0
	v_add_f32_e32 v0, 1.0, v0
	v_rcp_f32_e32 v35, v0
	v_mul_f32_e32 v0, 0xbfb8aa3b, v24
	v_exp_f32_e32 v0, v0
	v_pk_mul_f32 v[14:15], v[14:15], v[34:35]
	s_nop 0
	v_pk_mul_f32 v[178:179], v[14:15], v[14:15]
	v_add_f32_e32 v0, 1.0, v0
	v_rcp_f32_e32 v34, v0
	v_mul_f32_e32 v0, 0xbfb8aa3b, v25
	v_exp_f32_e32 v0, v0
	s_nop 0
	v_add_f32_e32 v0, 1.0, v0
	v_rcp_f32_e32 v35, v0
	v_mul_f32_e32 v0, 0xbfb8aa3b, v26
	v_exp_f32_e32 v0, v0
	v_pk_mul_f32 v[24:25], v[24:25], v[34:35]
	s_nop 0
	v_pk_mul_f32 v[34:35], v[24:25], v[24:25]
	v_add_f32_e32 v0, 1.0, v0
	v_rcp_f32_e32 v36, v0
	v_mul_f32_e32 v0, 0xbfb8aa3b, v27
	v_exp_f32_e32 v0, v0
	s_nop 0
	v_add_f32_e32 v0, 1.0, v0
	v_rcp_f32_e32 v37, v0
	v_mul_f32_e32 v0, 0xbfb8aa3b, v28
	v_exp_f32_e32 v0, v0
	v_pk_mul_f32 v[26:27], v[26:27], v[36:37]
	s_nop 0
	v_pk_mul_f32 v[36:37], v[26:27], v[26:27]
	v_add_f32_e32 v0, 1.0, v0
	v_rcp_f32_e32 v38, v0
	v_mul_f32_e32 v0, 0xbfb8aa3b, v29
	v_exp_f32_e32 v0, v0
	s_nop 0
	v_add_f32_e32 v0, 1.0, v0
	v_rcp_f32_e32 v39, v0
	v_mul_f32_e32 v0, 0xbfb8aa3b, v30
	v_exp_f32_e32 v0, v0
	v_pk_mul_f32 v[28:29], v[28:29], v[38:39]
	s_nop 0
	v_pk_mul_f32 v[38:39], v[28:29], v[28:29]
	v_add_f32_e32 v0, 1.0, v0
	v_rcp_f32_e32 v40, v0
	v_mul_f32_e32 v0, 0xbfb8aa3b, v31
	v_exp_f32_e32 v0, v0
	s_nop 0
	v_add_f32_e32 v0, 1.0, v0
	v_rcp_f32_e32 v41, v0
	v_add_f32_e32 v0, v172, v173
	v_add_f32_e32 v0, v174, v0
	v_add_f32_e32 v0, v175, v0
	v_add_f32_e32 v0, v176, v0
	v_add_f32_e32 v0, v177, v0
	v_add_f32_e32 v0, v178, v0
	v_add_f32_e32 v0, v179, v0
	v_add_f32_e32 v0, v0, v180
	v_add_f32_e32 v0, v181, v0
	v_add_f32_e32 v0, v182, v0
	v_add_f32_e32 v0, v183, v0
	v_add_f32_e32 v0, v184, v0
	v_add_f32_e32 v0, v185, v0
	v_add_f32_e32 v0, v186, v0
	v_add_f32_e32 v0, v187, v0
	v_add_f32_e32 v0, v0, v188
	v_add_f32_e32 v0, v189, v0
	v_add_f32_e32 v0, v190, v0
	v_add_f32_e32 v0, v191, v0
	v_add_f32_e32 v0, v192, v0
	v_add_f32_e32 v0, v193, v0
	v_add_f32_e32 v0, v194, v0
	v_add_f32_e32 v0, v195, v0
	v_add_f32_e32 v0, v0, v34
	v_add_f32_e32 v0, v35, v0
	v_add_f32_e32 v0, v36, v0
	v_add_f32_e32 v0, v37, v0
	v_pk_mul_f32 v[30:31], v[30:31], v[40:41]
	v_add_f32_e32 v0, v38, v0
	v_pk_mul_f32 v[40:41], v[30:31], v[30:31]
	v_add_f32_e32 v0, v39, v0
	v_add_f32_e32 v0, v40, v0
	v_add_f32_e32 v0, v41, v0
	ds_bpermute_b32 v34, v95, v0
	s_waitcnt lgkmcnt(0)
; __device__ __forceinline__ void conv32(const u16* __restrict__ src  , const float* cwl  ,
;                                        int row, int tglob, int col, int cl  , float (&y)[32]) {
;     ...
;     for (int i = 0; i < 4; ++i) {
;       const int dt = i - 3;
;       if (tglob + dt >= 0) {
;         uint4 xv = *(const uint4*)(src + (size_t)(row + dt) * 3072 + col + sb * 8);
;         float4 w0 = *(const float4*)(cwl + i * 128 + cl + sb * 8);
;         float4 w1 = *(const float4*)(cwl + i * 128 + cl + sb * 8 + 4);
; __device__ __forceinline__ void phase_dnprep(const Params& p, char* smem) {
;     ...
;       ss += __shfl_xor(ss, 1, 64); ss += __shfl_xor(ss, 2, 64);
;       float rn = rsqrtf(ss + NORM_EPS) * 0.08838834764831845f;
; #pragma unroll
;       for (int j = 0; j < 32; ++j) y[j] *= rn;
; #pragma unroll
;       for (int j = 0; j < 4; ++j) {
;         uint4 o;
;         o.x = pack2(y[j * 8 + 0], y[j * 8 + 1]); o.y = pack2(y[j * 8 + 2], y[j * 8 + 3]);
;         o.z = pack2(y[j * 8 + 4], y[j * 8 + 5]); o.w = pack2(y[j * 8 + 6], y[j * 8 + 7]);
;         *(uint4*)(Qs + tk * 136 + cq * 32 + j * 8) = o;
;       }
;       const int f = (tk >> 4) * 4 + cq;
; #pragma unroll
;       for (int qp = 0; qp < 4; ++qp) {
;         uint4 o;
;         o.x = pack2(y[qp * 4 + 0] * egc_t, y[qp * 4 + 1] * egc_t);
;         o.y = pack2(y[qp * 4 + 2] * egc_t, y[qp * 4 + 3] * egc_t);
;         o.z = pack2(y[16 + qp * 4 + 0] * egc_t, y[16 + qp * 4 + 1] * egc_t);
;         o.w = pack2(y[16 + qp * 4 + 2] * egc_t, y[16 + qp * 4 + 3] * egc_t);
;         *(uint4*)(rec + REC_QD + ((size_t)(f * 64 + (tk & 15) + 16 * qp)) * 16) = o;
;       }
	v_add_f32_e32 v0, v0, v34
	ds_bpermute_b32 v34, v96, v0
	s_waitcnt lgkmcnt(0)
	v_add_f32_e32 v0, v0, v34
	v_add_f32_e32 v0, 0x358637bd, v0
	v_cmp_gt_f32_e64 s[96:97], s18, v0
	v_mul_f32_e32 v34, 0x4b800000, v0
	s_nop 0
	v_cndmask_b32_e64 v0, v0, v34, s[96:97]
	v_rsq_f32_e32 v0, v0
	s_nop 0
	v_mul_f32_e32 v34, 0x45800000, v0
	v_cndmask_b32_e64 v0, v0, v34, s[96:97]
	v_mul_f32_e32 v0, 0x3db504f3, v0
	v_pk_mul_f32 v[8:9], v[8:9], v[0:1] op_sel_hi:[1,0]
	v_pk_mul_f32 v[10:11], v[10:11], v[0:1] op_sel_hi:[1,0]
	v_pk_mul_f32 v[12:13], v[12:13], v[0:1] op_sel_hi:[1,0]
	v_pk_mul_f32 v[14:15], v[14:15], v[0:1] op_sel_hi:[1,0]
	v_pk_mul_f32 v[16:17], v[16:17], v[0:1] op_sel_hi:[1,0]
	v_pk_mul_f32 v[18:19], v[18:19], v[0:1] op_sel_hi:[1,0]
	v_pk_mul_f32 v[20:21], v[20:21], v[0:1] op_sel_hi:[1,0]
	v_pk_mul_f32 v[22:23], v[22:23], v[0:1] op_sel_hi:[1,0]
	v_pk_mul_f32 v[34:35], v[2:3], v[0:1] op_sel_hi:[1,0]
	v_pk_mul_f32 v[36:37], v[4:5], v[0:1] op_sel_hi:[1,0]
	v_cvt_pk_bf16_f32 v2, v8, v9
	v_cvt_pk_bf16_f32 v3, v10, v11
	v_cvt_pk_bf16_f32 v4, v12, v13
	v_cvt_pk_bf16_f32 v5, v14, v15
	v_pk_mul_f32 v[6:7], v[6:7], v[0:1] op_sel_hi:[1,0]
	v_pk_mul_f32 v[32:33], v[32:33], v[0:1] op_sel_hi:[1,0]
	ds_write_b128 v97, v[2:5]
	v_cvt_pk_bf16_f32 v2, v16, v17
	v_cvt_pk_bf16_f32 v3, v18, v19
	v_cvt_pk_bf16_f32 v4, v20, v21
	v_cvt_pk_bf16_f32 v5, v22, v23
	v_pk_mul_f32 v[24:25], v[24:25], v[0:1] op_sel_hi:[1,0]
	v_pk_mul_f32 v[26:27], v[26:27], v[0:1] op_sel_hi:[1,0]
	v_pk_mul_f32 v[28:29], v[28:29], v[0:1] op_sel_hi:[1,0]
	v_pk_mul_f32 v[30:31], v[30:31], v[0:1] op_sel_hi:[1,0]
	ds_write_b128 v97, v[2:5] offset:16
	v_cvt_pk_bf16_f32 v2, v34, v35
	v_cvt_pk_bf16_f32 v3, v36, v37
	v_cvt_pk_bf16_f32 v4, v6, v7
	v_cvt_pk_bf16_f32 v5, v32, v33
	ds_write_b128 v97, v[2:5] offset:32
	v_cvt_pk_bf16_f32 v2, v24, v25
	v_cvt_pk_bf16_f32 v3, v26, v27
	v_cvt_pk_bf16_f32 v4, v28, v29
	v_cvt_pk_bf16_f32 v5, v30, v31
	v_mov_b32_e32 v0, v85
	ds_write_b128 v97, v[2:5] offset:48
	s_add_u32 s96, s8, 0x4000
	v_pk_mul_f32 v[2:3], v[0:1], v[8:9] op_sel_hi:[0,1]
	v_pk_mul_f32 v[4:5], v[0:1], v[10:11] op_sel_hi:[0,1]
	s_addc_u32 s97, s9, 0
	v_cvt_pk_bf16_f32 v2, v2, v3
	v_cvt_pk_bf16_f32 v3, v4, v5
	v_pk_mul_f32 v[4:5], v[0:1], v[34:35] op_sel_hi:[0,1]
	v_pk_mul_f32 v[8:9], v[0:1], v[36:37] op_sel_hi:[0,1]
	v_cvt_pk_bf16_f32 v4, v4, v5
	v_cvt_pk_bf16_f32 v5, v8, v9
	v_lshl_add_u64 v[8:9], s[96:97], 0, v[44:45]
	global_store_dwordx4 v[8:9], v[2:5], off
	s_nop 1
	v_pk_mul_f32 v[2:3], v[0:1], v[12:13] op_sel_hi:[0,1]
	v_pk_mul_f32 v[4:5], v[0:1], v[14:15] op_sel_hi:[0,1]
	v_cvt_pk_bf16_f32 v2, v2, v3
	v_cvt_pk_bf16_f32 v3, v4, v5
	v_pk_mul_f32 v[4:5], v[0:1], v[6:7] op_sel_hi:[0,1]
	v_pk_mul_f32 v[6:7], v[0:1], v[32:33] op_sel_hi:[0,1]
	v_cvt_pk_bf16_f32 v4, v4, v5
	v_cvt_pk_bf16_f32 v5, v6, v7
	v_lshl_add_u64 v[6:7], s[96:97], 0, v[46:47]
	global_store_dwordx4 v[6:7], v[2:5], off
	v_pk_mul_f32 v[6:7], v[0:1], v[26:27] op_sel_hi:[0,1]
	s_nop 0
	v_pk_mul_f32 v[2:3], v[0:1], v[16:17] op_sel_hi:[0,1]
	v_pk_mul_f32 v[4:5], v[0:1], v[18:19] op_sel_hi:[0,1]
	v_cvt_pk_bf16_f32 v2, v2, v3
	v_cvt_pk_bf16_f32 v3, v4, v5
	v_pk_mul_f32 v[4:5], v[0:1], v[24:25] op_sel_hi:[0,1]
	v_cvt_pk_bf16_f32 v4, v4, v5
	v_cvt_pk_bf16_f32 v5, v6, v7
	v_lshl_add_u64 v[6:7], s[96:97], 0, v[48:49]
	global_store_dwordx4 v[6:7], v[2:5], off
	v_pk_mul_f32 v[6:7], v[0:1], v[30:31] op_sel_hi:[0,1]
	s_nop 0
	v_pk_mul_f32 v[2:3], v[0:1], v[20:21] op_sel_hi:[0,1]
	v_pk_mul_f32 v[4:5], v[0:1], v[22:23] op_sel_hi:[0,1]
	v_cvt_pk_bf16_f32 v2, v2, v3
	v_cvt_pk_bf16_f32 v3, v4, v5
	v_pk_mul_f32 v[4:5], v[0:1], v[28:29] op_sel_hi:[0,1]
	v_cvt_pk_bf16_f32 v4, v4, v5
	v_cvt_pk_bf16_f32 v5, v6, v7
	v_lshl_add_u64 v[6:7], s[96:97], 0, v[50:51]
	global_store_dwordx4 v[6:7], v[2:5], off
	v_mov_b32_e32 v6, v1
	v_mov_b32_e32 v7, v1
	v_mov_b32_e32 v0, v1
	v_mov_b32_e32 v2, v1
	v_mov_b32_e32 v3, v1
	v_mov_b32_e32 v4, v1
	v_mov_b32_e32 v5, v1
	v_mov_b64_e32 v[14:15], v[6:7]
	v_mov_b64_e32 v[12:13], v[4:5]
	v_mov_b64_e32 v[10:11], v[2:3]
	v_mov_b64_e32 v[8:9], v[0:1]
	s_and_saveexec_b64 s[100:101], vcc
	v_mad_i64_i32 v[250:251], s[98:99], v169, s63, v[86:87]
	global_load_dwordx4 v[196:199], v[250:251], off offset:2048
	global_load_dwordx4 v[212:215], v[250:251], off offset:2064
	global_load_dwordx4 v[234:237], v[250:251], off offset:2080
	s_or_b64 exec, exec, s[100:101]
	s_and_saveexec_b64 s[100:101], s[90:91]
	v_mad_i64_i32 v[250:251], s[98:99], v170, s63, v[86:87]
	global_load_dwordx4 v[200:203], v[250:251], off offset:2048
	global_load_dwordx4 v[220:223], v[250:251], off offset:2064
	global_load_dwordx4 v[238:241], v[250:251], off offset:2080
	s_or_b64 exec, exec, s[100:101]
	s_and_saveexec_b64 s[100:101], s[92:93]
	v_mad_i64_i32 v[250:251], s[98:99], v171, s63, v[86:87]
	global_load_dwordx4 v[204:207], v[250:251], off offset:2048
	global_load_dwordx4 v[224:227], v[250:251], off offset:2064
	global_load_dwordx4 v[242:245], v[250:251], off offset:2080
	s_or_b64 exec, exec, s[100:101]
	s_and_saveexec_b64 s[100:101], s[94:95]
	v_mad_i64_i32 v[250:251], s[98:99], v168, s63, v[86:87]
	global_load_dwordx4 v[208:211], v[250:251], off offset:2048
	global_load_dwordx4 v[230:233], v[250:251], off offset:2064
	global_load_dwordx4 v[246:249], v[250:251], off offset:2080
	s_or_b64 exec, exec, s[100:101]
	s_waitcnt vmcnt(0)
	s_and_saveexec_b64 s[96:97], vcc
	s_cbranch_execnz .LBB0_832
	s_or_b64 exec, exec, s[96:97]
	s_and_saveexec_b64 s[96:97], s[90:91]
	s_cbranch_execnz .LBB0_833

; __device__ __forceinline__ float lo_bf(unsigned u) { return __uint_as_float(u << 16); }
; __device__ __forceinline__ float hi_bf(unsigned u) { return __uint_as_float(u & 0xffff0000u); }
; __device__ __forceinline__ void conv32(const u16* __restrict__ src  , const float* cwl  ,
;                                        int row, int tglob, int col, int cl  , float (&y)[32]) {
;     ...
;     for (int i = 0; i < 4; ++i) {
;       const int dt = i - 3;
;       if (tglob + dt >= 0) {
;         uint4 xv = *(const uint4*)(src + (size_t)(row + dt) * 3072 + col + sb * 8);
;         float4 w0 = *(const float4*)(cwl + i * 128 + cl + sb * 8);
;         float4 w1 = *(const float4*)(cwl + i * 128 + cl + sb * 8 + 4);
;         acc[0] += w0.x * lo_bf(xv.x); acc[1] += w0.y * hi_bf(xv.x);
;         acc[2] += w0.z * lo_bf(xv.y); acc[3] += w0.w * hi_bf(xv.y);
;         acc[4] += w1.x * lo_bf(xv.z); acc[5] += w1.y * hi_bf(xv.z);
;         acc[6] += w1.z * lo_bf(xv.w); acc[7] += w1.w * hi_bf(xv.w);
;       }
.LBB0_726:
	v_mov_b64_e32 v[2:3], v[208:209]
	v_mov_b64_e32 v[4:5], v[210:211]
	ds_read_b128 v[16:19], v94 offset:56832
	ds_read_b128 v[20:23], v94 offset:56848
	s_waitcnt vmcnt(0)
	v_lshlrev_b32_e32 v6, 16, v2
	v_and_b32_e32 v7, 0xffff0000, v2
	v_lshlrev_b32_e32 v2, 16, v3
	v_and_b32_e32 v3, 0xffff0000, v3
	v_lshlrev_b32_e32 v24, 16, v4
	v_and_b32_e32 v25, 0xffff0000, v4
	v_lshlrev_b32_e32 v4, 16, v5
	v_and_b32_e32 v5, 0xffff0000, v5
	s_waitcnt lgkmcnt(0)
	v_pk_fma_f32 v[14:15], v[22:23], v[4:5], v[14:15]
	v_pk_fma_f32 v[12:13], v[20:21], v[24:25], v[12:13]
	v_pk_fma_f32 v[10:11], v[18:19], v[2:3], v[10:11]
	v_pk_fma_f32 v[8:9], v[16:17], v[6:7], v[8:9]

; __device__ __forceinline__ float lo_bf(unsigned u) { return __uint_as_float(u << 16); }
; __device__ __forceinline__ float hi_bf(unsigned u) { return __uint_as_float(u & 0xffff0000u); }
; __device__ __forceinline__ void conv32(const u16* __restrict__ src  , const float* cwl  ,
;                                        int row, int tglob, int col, int cl  , float (&y)[32]) {
;     ...
;     for (int i = 0; i < 4; ++i) {
;       const int dt = i - 3;
;       if (tglob + dt >= 0) {
;         uint4 xv = *(const uint4*)(src + (size_t)(row + dt) * 3072 + col + sb * 8);
;         float4 w0 = *(const float4*)(cwl + i * 128 + cl + sb * 8);
;         float4 w1 = *(const float4*)(cwl + i * 128 + cl + sb * 8 + 4);
;         acc[0] += w0.x * lo_bf(xv.x); acc[1] += w0.y * hi_bf(xv.x);
;         acc[2] += w0.z * lo_bf(xv.y); acc[3] += w0.w * hi_bf(xv.y);
;         acc[4] += w1.x * lo_bf(xv.z); acc[5] += w1.y * hi_bf(xv.z);
;         acc[6] += w1.z * lo_bf(xv.w); acc[7] += w1.w * hi_bf(xv.w);
;       }
.LBB0_731:
	v_mov_b64_e32 v[2:3], v[230:231]
	v_mov_b64_e32 v[4:5], v[232:233]
	ds_read_b128 v[24:27], v94 offset:56864
	ds_read_b128 v[28:31], v94 offset:56880
	s_waitcnt vmcnt(0)
	v_lshlrev_b32_e32 v6, 16, v2
	v_and_b32_e32 v7, 0xffff0000, v2
	v_lshlrev_b32_e32 v2, 16, v3
	v_and_b32_e32 v3, 0xffff0000, v3
	v_lshlrev_b32_e32 v32, 16, v4
	v_and_b32_e32 v33, 0xffff0000, v4
	v_lshlrev_b32_e32 v4, 16, v5
	v_and_b32_e32 v5, 0xffff0000, v5
	s_waitcnt lgkmcnt(0)
	v_pk_fma_f32 v[22:23], v[30:31], v[4:5], v[22:23]
	v_pk_fma_f32 v[20:21], v[28:29], v[32:33], v[20:21]
	v_pk_fma_f32 v[18:19], v[26:27], v[2:3], v[18:19]
	v_pk_fma_f32 v[16:17], v[24:25], v[6:7], v[16:17]

; __device__ __forceinline__ float lo_bf(unsigned u) { return __uint_as_float(u << 16); }
; __device__ __forceinline__ float hi_bf(unsigned u) { return __uint_as_float(u & 0xffff0000u); }
; __device__ __forceinline__ void conv32(const u16* __restrict__ src  , const float* cwl  ,
;                                        int row, int tglob, int col, int cl  , float (&y)[32]) {
;     ...
;     for (int i = 0; i < 4; ++i) {
;       const int dt = i - 3;
;       if (tglob + dt >= 0) {
;         uint4 xv = *(const uint4*)(src + (size_t)(row + dt) * 3072 + col + sb * 8);
;         float4 w0 = *(const float4*)(cwl + i * 128 + cl + sb * 8);
;         float4 w1 = *(const float4*)(cwl + i * 128 + cl + sb * 8 + 4);
;         acc[0] += w0.x * lo_bf(xv.x); acc[1] += w0.y * hi_bf(xv.x);
;         acc[2] += w0.z * lo_bf(xv.y); acc[3] += w0.w * hi_bf(xv.y);
;         acc[4] += w1.x * lo_bf(xv.z); acc[5] += w1.y * hi_bf(xv.z);
;         acc[6] += w1.z * lo_bf(xv.w); acc[7] += w1.w * hi_bf(xv.w);
;       }
.LBB0_736:
	v_mov_b64_e32 v[2:3], v[246:247]
	v_mov_b64_e32 v[4:5], v[248:249]
	ds_read_b128 v[32:35], v94 offset:56896
	ds_read_b128 v[36:39], v94 offset:56912
	s_waitcnt vmcnt(0)
	v_lshlrev_b32_e32 v6, 16, v2
	v_and_b32_e32 v7, 0xffff0000, v2
	v_lshlrev_b32_e32 v2, 16, v3
	v_and_b32_e32 v3, 0xffff0000, v3
	v_lshlrev_b32_e32 v40, 16, v4
	v_and_b32_e32 v41, 0xffff0000, v4
	v_lshlrev_b32_e32 v4, 16, v5
	v_and_b32_e32 v5, 0xffff0000, v5
	s_waitcnt lgkmcnt(0)
	v_pk_fma_f32 v[30:31], v[38:39], v[4:5], v[30:31]
	v_pk_fma_f32 v[28:29], v[36:37], v[40:41], v[28:29]
	v_pk_fma_f32 v[26:27], v[34:35], v[2:3], v[26:27]
	v_pk_fma_f32 v[24:25], v[32:33], v[6:7], v[24:25]

; __device__ __forceinline__ float lo_bf(unsigned u) { return __uint_as_float(u << 16); }
; __device__ __forceinline__ float hi_bf(unsigned u) { return __uint_as_float(u & 0xffff0000u); }
; __device__ __forceinline__ void conv32(const u16* __restrict__ src  , const float* cwl  ,
;                                        int row, int tglob, int col, int cl  , float (&y)[32]) {
;     ...
;     for (int i = 0; i < 4; ++i) {
;       const int dt = i - 3;
;       if (tglob + dt >= 0) {
;         uint4 xv = *(const uint4*)(src + (size_t)(row + dt) * 3072 + col + sb * 8);
;         float4 w0 = *(const float4*)(cwl + i * 128 + cl + sb * 8);
;         float4 w1 = *(const float4*)(cwl + i * 128 + cl + sb * 8 + 4);
;         acc[0] += w0.x * lo_bf(xv.x); acc[1] += w0.y * hi_bf(xv.x);
;         acc[2] += w0.z * lo_bf(xv.y); acc[3] += w0.w * hi_bf(xv.y);
;         acc[4] += w1.x * lo_bf(xv.z); acc[5] += w1.y * hi_bf(xv.z);
;         acc[6] += w1.z * lo_bf(xv.w); acc[7] += w1.w * hi_bf(xv.w);
;       }
.LBB0_823:
	v_mov_b64_e32 v[2:3], v[212:213]
	v_mov_b64_e32 v[4:5], v[214:215]
	ds_read_b128 v[16:19], v94 offset:53280
	ds_read_b128 v[20:23], v94 offset:53296
	s_waitcnt vmcnt(0)
	v_lshlrev_b32_e32 v6, 16, v2
	v_and_b32_e32 v7, 0xffff0000, v2
	v_lshlrev_b32_e32 v2, 16, v3
	v_and_b32_e32 v3, 0xffff0000, v3
	v_lshlrev_b32_e32 v24, 16, v4
	v_and_b32_e32 v25, 0xffff0000, v4
	v_lshlrev_b32_e32 v4, 16, v5
	v_and_b32_e32 v5, 0xffff0000, v5
	s_waitcnt lgkmcnt(0)
	v_pk_fma_f32 v[22:23], v[22:23], v[4:5], 0 op_sel_hi:[1,1,0]
	v_pk_fma_f32 v[20:21], v[20:21], v[24:25], 0 op_sel_hi:[1,1,0]
	v_pk_fma_f32 v[18:19], v[18:19], v[2:3], 0 op_sel_hi:[1,1,0]
	v_pk_fma_f32 v[16:17], v[16:17], v[6:7], 0 op_sel_hi:[1,1,0]
	s_or_b64 exec, exec, s[8:9]
	s_and_saveexec_b64 s[8:9], s[90:91]
	s_cbranch_execz .LBB0_709
.LBB0_824:
	v_mov_b64_e32 v[2:3], v[220:221]
	v_mov_b64_e32 v[4:5], v[222:223]
	ds_read_b128 v[24:27], v94 offset:53792
	ds_read_b128 v[28:31], v94 offset:53808
	s_waitcnt vmcnt(0)
	v_lshlrev_b32_e32 v6, 16, v2
	v_and_b32_e32 v7, 0xffff0000, v2
	v_lshlrev_b32_e32 v2, 16, v3
	v_and_b32_e32 v3, 0xffff0000, v3
	v_lshlrev_b32_e32 v32, 16, v4
	v_and_b32_e32 v33, 0xffff0000, v4
	v_lshlrev_b32_e32 v4, 16, v5
	v_and_b32_e32 v5, 0xffff0000, v5
	s_waitcnt lgkmcnt(0)
	v_pk_fma_f32 v[22:23], v[30:31], v[4:5], v[22:23]
	v_pk_fma_f32 v[20:21], v[28:29], v[32:33], v[20:21]
	v_pk_fma_f32 v[18:19], v[26:27], v[2:3], v[18:19]
	v_pk_fma_f32 v[16:17], v[24:25], v[6:7], v[16:17]
	s_or_b64 exec, exec, s[8:9]
	s_and_saveexec_b64 s[8:9], s[92:93]
	s_cbranch_execz .LBB0_710
.LBB0_825:
	v_mov_b64_e32 v[2:3], v[224:225]
	v_mov_b64_e32 v[4:5], v[226:227]
	ds_read_b128 v[24:27], v94 offset:54304
	ds_read_b128 v[28:31], v94 offset:54320
	s_waitcnt vmcnt(0)
	v_lshlrev_b32_e32 v6, 16, v2
	v_and_b32_e32 v7, 0xffff0000, v2
	v_lshlrev_b32_e32 v2, 16, v3
	v_and_b32_e32 v3, 0xffff0000, v3
	v_lshlrev_b32_e32 v32, 16, v4
	v_and_b32_e32 v33, 0xffff0000, v4
	v_lshlrev_b32_e32 v4, 16, v5
	v_and_b32_e32 v5, 0xffff0000, v5
	s_waitcnt lgkmcnt(0)
	v_pk_fma_f32 v[22:23], v[30:31], v[4:5], v[22:23]
	v_pk_fma_f32 v[20:21], v[28:29], v[32:33], v[20:21]
	v_pk_fma_f32 v[18:19], v[26:27], v[2:3], v[18:19]
	v_pk_fma_f32 v[16:17], v[24:25], v[6:7], v[16:17]
	s_or_b64 exec, exec, s[8:9]
	s_and_saveexec_b64 s[8:9], s[94:95]
	s_cbranch_execnz .LBB0_711
	s_branch .LBB0_712
.LBB0_826:
	v_mov_b64_e32 v[2:3], v[234:235]
	v_mov_b64_e32 v[4:5], v[236:237]
	ds_read_b128 v[24:27], v94 offset:53312
	ds_read_b128 v[28:31], v94 offset:53328
	s_waitcnt vmcnt(0)
	v_lshlrev_b32_e32 v6, 16, v2
	v_and_b32_e32 v7, 0xffff0000, v2
	v_lshlrev_b32_e32 v2, 16, v3
	v_and_b32_e32 v3, 0xffff0000, v3
	v_lshlrev_b32_e32 v32, 16, v4
	v_and_b32_e32 v33, 0xffff0000, v4
	v_lshlrev_b32_e32 v4, 16, v5
	v_and_b32_e32 v5, 0xffff0000, v5
	s_waitcnt lgkmcnt(0)
	v_pk_fma_f32 v[38:39], v[30:31], v[4:5], 0 op_sel_hi:[1,1,0]
	v_pk_fma_f32 v[36:37], v[28:29], v[32:33], 0 op_sel_hi:[1,1,0]
	v_pk_fma_f32 v[34:35], v[26:27], v[2:3], 0 op_sel_hi:[1,1,0]
	v_pk_fma_f32 v[32:33], v[24:25], v[6:7], 0 op_sel_hi:[1,1,0]
	s_or_b64 exec, exec, s[8:9]
	s_and_saveexec_b64 s[8:9], s[90:91]
	s_cbranch_execz .LBB0_714
.LBB0_827:
	v_mov_b64_e32 v[2:3], v[238:239]
	v_mov_b64_e32 v[4:5], v[240:241]
	ds_read_b128 v[24:27], v94 offset:53824
	ds_read_b128 v[28:31], v94 offset:53840
	s_waitcnt vmcnt(0)
	v_lshlrev_b32_e32 v6, 16, v2
	v_and_b32_e32 v7, 0xffff0000, v2
	v_lshlrev_b32_e32 v2, 16, v3
	v_and_b32_e32 v3, 0xffff0000, v3
	v_lshlrev_b32_e32 v40, 16, v4
	v_and_b32_e32 v41, 0xffff0000, v4
	v_lshlrev_b32_e32 v4, 16, v5
	v_and_b32_e32 v5, 0xffff0000, v5
	s_waitcnt lgkmcnt(0)
	v_pk_fma_f32 v[38:39], v[30:31], v[4:5], v[38:39]
	v_pk_fma_f32 v[36:37], v[28:29], v[40:41], v[36:37]
	v_pk_fma_f32 v[34:35], v[26:27], v[2:3], v[34:35]
	v_pk_fma_f32 v[32:33], v[24:25], v[6:7], v[32:33]
	s_or_b64 exec, exec, s[8:9]
	s_and_saveexec_b64 s[8:9], s[92:93]
	s_cbranch_execz .LBB0_715
.LBB0_828:
	v_mov_b64_e32 v[2:3], v[242:243]
	v_mov_b64_e32 v[4:5], v[244:245]
	ds_read_b128 v[24:27], v94 offset:54336
	ds_read_b128 v[28:31], v94 offset:54352
	s_waitcnt vmcnt(0)
	v_lshlrev_b32_e32 v6, 16, v2
	v_and_b32_e32 v7, 0xffff0000, v2
	v_lshlrev_b32_e32 v2, 16, v3
	v_and_b32_e32 v3, 0xffff0000, v3
	v_lshlrev_b32_e32 v40, 16, v4
	v_and_b32_e32 v41, 0xffff0000, v4
	v_lshlrev_b32_e32 v4, 16, v5
	v_and_b32_e32 v5, 0xffff0000, v5
	s_waitcnt lgkmcnt(0)
	v_pk_fma_f32 v[38:39], v[30:31], v[4:5], v[38:39]
	v_pk_fma_f32 v[36:37], v[28:29], v[40:41], v[36:37]
	v_pk_fma_f32 v[34:35], v[26:27], v[2:3], v[34:35]
	v_pk_fma_f32 v[32:33], v[24:25], v[6:7], v[32:33]
	s_or_b64 exec, exec, s[8:9]
	s_and_saveexec_b64 s[8:9], s[94:95]
	s_cbranch_execnz .LBB0_716
	s_branch .LBB0_717

; __device__ __forceinline__ float lo_bf(unsigned u) { return __uint_as_float(u << 16); }
; __device__ __forceinline__ float hi_bf(unsigned u) { return __uint_as_float(u & 0xffff0000u); }
; __device__ __forceinline__ void conv32(const u16* __restrict__ src  , const float* cwl  ,
;                                        int row, int tglob, int col, int cl  , float (&y)[32]) {
;     ...
;   for (int sb = 0; sb < 4; ++sb) {
;     float acc[8];
; #pragma unroll
;     for (int j = 0; j < 8; ++j) acc[j] = 0.f;
; #pragma unroll
;     for (int i = 0; i < 4; ++i) {
;       const int dt = i - 3;
;       if (tglob + dt >= 0) {
;         uint4 xv = *(const uint4*)(src + (size_t)(row + dt) * 3072 + col + sb * 8);
;         float4 w0 = *(const float4*)(cwl + i * 128 + cl + sb * 8);
;         float4 w1 = *(const float4*)(cwl + i * 128 + cl + sb * 8 + 4);
;         acc[0] += w0.x * lo_bf(xv.x); acc[1] += w0.y * hi_bf(xv.x);
;         acc[2] += w0.z * lo_bf(xv.y); acc[3] += w0.w * hi_bf(xv.y);
;         acc[4] += w1.x * lo_bf(xv.z); acc[5] += w1.y * hi_bf(xv.z);
;         acc[6] += w1.z * lo_bf(xv.w); acc[7] += w1.w * hi_bf(xv.w);
;       }
.LBB0_832:
	v_mov_b64_e32 v[2:3], v[196:197]
	v_mov_b64_e32 v[4:5], v[198:199]
	ds_read_b128 v[6:9], v94 offset:55296
	ds_read_b128 v[10:13], v94 offset:55312
	s_waitcnt vmcnt(0)
	v_lshlrev_b32_e32 v16, 16, v2
	v_and_b32_e32 v17, 0xffff0000, v2
	v_lshlrev_b32_e32 v2, 16, v3
	v_and_b32_e32 v3, 0xffff0000, v3
	v_lshlrev_b32_e32 v18, 16, v4
	v_and_b32_e32 v19, 0xffff0000, v4
	v_lshlrev_b32_e32 v4, 16, v5
	v_and_b32_e32 v5, 0xffff0000, v5
	s_waitcnt lgkmcnt(0)
	v_pk_fma_f32 v[14:15], v[12:13], v[4:5], 0 op_sel_hi:[1,1,0]
	v_pk_fma_f32 v[12:13], v[10:11], v[18:19], 0 op_sel_hi:[1,1,0]
	v_pk_fma_f32 v[10:11], v[8:9], v[2:3], 0 op_sel_hi:[1,1,0]
	v_pk_fma_f32 v[8:9], v[6:7], v[16:17], 0 op_sel_hi:[1,1,0]
	s_or_b64 exec, exec, s[96:97]
	s_and_saveexec_b64 s[96:97], s[90:91]
	s_cbranch_execz .LBB0_724
.LBB0_833:
	v_mov_b64_e32 v[2:3], v[200:201]
	v_mov_b64_e32 v[4:5], v[202:203]
	ds_read_b128 v[16:19], v94 offset:55808
	ds_read_b128 v[20:23], v94 offset:55824
	s_waitcnt vmcnt(0)
	v_lshlrev_b32_e32 v6, 16, v2
	v_and_b32_e32 v7, 0xffff0000, v2
	v_lshlrev_b32_e32 v2, 16, v3
	v_and_b32_e32 v3, 0xffff0000, v3
	v_lshlrev_b32_e32 v24, 16, v4
	v_and_b32_e32 v25, 0xffff0000, v4
	v_lshlrev_b32_e32 v4, 16, v5
	v_and_b32_e32 v5, 0xffff0000, v5
	s_waitcnt lgkmcnt(0)
	v_pk_fma_f32 v[14:15], v[22:23], v[4:5], v[14:15]
	v_pk_fma_f32 v[12:13], v[20:21], v[24:25], v[12:13]
	v_pk_fma_f32 v[10:11], v[18:19], v[2:3], v[10:11]
	v_pk_fma_f32 v[8:9], v[16:17], v[6:7], v[8:9]
	s_or_b64 exec, exec, s[96:97]
	s_and_saveexec_b64 s[96:97], s[92:93]
	s_cbranch_execz .LBB0_725
.LBB0_834:
	v_mov_b64_e32 v[2:3], v[204:205]
	v_mov_b64_e32 v[4:5], v[206:207]
	ds_read_b128 v[16:19], v94 offset:56320
	ds_read_b128 v[20:23], v94 offset:56336
	s_waitcnt vmcnt(0)
	v_lshlrev_b32_e32 v6, 16, v2
	v_and_b32_e32 v7, 0xffff0000, v2
	v_lshlrev_b32_e32 v2, 16, v3
	v_and_b32_e32 v3, 0xffff0000, v3
	v_lshlrev_b32_e32 v24, 16, v4
	v_and_b32_e32 v25, 0xffff0000, v4
	v_lshlrev_b32_e32 v4, 16, v5
	v_and_b32_e32 v5, 0xffff0000, v5
	s_waitcnt lgkmcnt(0)
	v_pk_fma_f32 v[14:15], v[22:23], v[4:5], v[14:15]
	v_pk_fma_f32 v[12:13], v[20:21], v[24:25], v[12:13]
	v_pk_fma_f32 v[10:11], v[18:19], v[2:3], v[10:11]
	v_pk_fma_f32 v[8:9], v[16:17], v[6:7], v[8:9]
	s_or_b64 exec, exec, s[96:97]
	s_and_saveexec_b64 s[96:97], s[94:95]
	s_cbranch_execnz .LBB0_726
	s_branch .LBB0_727
.LBB0_835:
	v_mov_b64_e32 v[2:3], v[212:213]
	v_mov_b64_e32 v[4:5], v[214:215]
	ds_read_b128 v[16:19], v94 offset:55328
	ds_read_b128 v[20:23], v94 offset:55344
	s_waitcnt vmcnt(0)
	v_lshlrev_b32_e32 v6, 16, v2
	v_and_b32_e32 v7, 0xffff0000, v2
	v_lshlrev_b32_e32 v2, 16, v3
	v_and_b32_e32 v3, 0xffff0000, v3
	v_lshlrev_b32_e32 v24, 16, v4
	v_and_b32_e32 v25, 0xffff0000, v4
	v_lshlrev_b32_e32 v4, 16, v5
	v_and_b32_e32 v5, 0xffff0000, v5
	s_waitcnt lgkmcnt(0)
	v_pk_fma_f32 v[22:23], v[22:23], v[4:5], 0 op_sel_hi:[1,1,0]
	v_pk_fma_f32 v[20:21], v[20:21], v[24:25], 0 op_sel_hi:[1,1,0]
	v_pk_fma_f32 v[18:19], v[18:19], v[2:3], 0 op_sel_hi:[1,1,0]
	v_pk_fma_f32 v[16:17], v[16:17], v[6:7], 0 op_sel_hi:[1,1,0]
	s_or_b64 exec, exec, s[96:97]
	s_and_saveexec_b64 s[96:97], s[90:91]
	s_cbranch_execz .LBB0_729
; __device__ __forceinline__ float lo_bf(unsigned u) { return __uint_as_float(u << 16); }
; __device__ __forceinline__ float hi_bf(unsigned u) { return __uint_as_float(u & 0xffff0000u); }
; __device__ __forceinline__ void conv32(const u16* __restrict__ src  , const float* cwl  ,
;                                        int row, int tglob, int col, int cl  , float (&y)[32]) {
;     ...
;   for (int sb = 0; sb < 4; ++sb) {
;     float acc[8];
; #pragma unroll
;     for (int j = 0; j < 8; ++j) acc[j] = 0.f;
; #pragma unroll
;     for (int i = 0; i < 4; ++i) {
;       const int dt = i - 3;
;       if (tglob + dt >= 0) {
;         uint4 xv = *(const uint4*)(src + (size_t)(row + dt) * 3072 + col + sb * 8);
;         float4 w0 = *(const float4*)(cwl + i * 128 + cl + sb * 8);
;         float4 w1 = *(const float4*)(cwl + i * 128 + cl + sb * 8 + 4);
;         acc[0] += w0.x * lo_bf(xv.x); acc[1] += w0.y * hi_bf(xv.x);
;         acc[2] += w0.z * lo_bf(xv.y); acc[3] += w0.w * hi_bf(xv.y);
;         acc[4] += w1.x * lo_bf(xv.z); acc[5] += w1.y * hi_bf(xv.z);
;         acc[6] += w1.z * lo_bf(xv.w); acc[7] += w1.w * hi_bf(xv.w);
;       }
.LBB0_836:
	v_mov_b64_e32 v[2:3], v[220:221]
	v_mov_b64_e32 v[4:5], v[222:223]
	ds_read_b128 v[24:27], v94 offset:55840
	ds_read_b128 v[28:31], v94 offset:55856
	s_waitcnt vmcnt(0)
	v_lshlrev_b32_e32 v6, 16, v2
	v_and_b32_e32 v7, 0xffff0000, v2
	v_lshlrev_b32_e32 v2, 16, v3
	v_and_b32_e32 v3, 0xffff0000, v3
	v_lshlrev_b32_e32 v32, 16, v4
	v_and_b32_e32 v33, 0xffff0000, v4
	v_lshlrev_b32_e32 v4, 16, v5
	v_and_b32_e32 v5, 0xffff0000, v5
	s_waitcnt lgkmcnt(0)
	v_pk_fma_f32 v[22:23], v[30:31], v[4:5], v[22:23]
	v_pk_fma_f32 v[20:21], v[28:29], v[32:33], v[20:21]
	v_pk_fma_f32 v[18:19], v[26:27], v[2:3], v[18:19]
	v_pk_fma_f32 v[16:17], v[24:25], v[6:7], v[16:17]
	s_or_b64 exec, exec, s[96:97]
	s_and_saveexec_b64 s[96:97], s[92:93]
	s_cbranch_execz .LBB0_730
.LBB0_837:
	v_mov_b64_e32 v[2:3], v[224:225]
	v_mov_b64_e32 v[4:5], v[226:227]
	ds_read_b128 v[24:27], v94 offset:56352
	ds_read_b128 v[28:31], v94 offset:56368
	s_waitcnt vmcnt(0)
	v_lshlrev_b32_e32 v6, 16, v2
	v_and_b32_e32 v7, 0xffff0000, v2
	v_lshlrev_b32_e32 v2, 16, v3
	v_and_b32_e32 v3, 0xffff0000, v3
	v_lshlrev_b32_e32 v32, 16, v4
	v_and_b32_e32 v33, 0xffff0000, v4
	v_lshlrev_b32_e32 v4, 16, v5
	v_and_b32_e32 v5, 0xffff0000, v5
	s_waitcnt lgkmcnt(0)
	v_pk_fma_f32 v[22:23], v[30:31], v[4:5], v[22:23]
	v_pk_fma_f32 v[20:21], v[28:29], v[32:33], v[20:21]
	v_pk_fma_f32 v[18:19], v[26:27], v[2:3], v[18:19]
	v_pk_fma_f32 v[16:17], v[24:25], v[6:7], v[16:17]
	s_or_b64 exec, exec, s[96:97]
	s_and_saveexec_b64 s[96:97], s[94:95]
	s_cbranch_execnz .LBB0_731
	s_branch .LBB0_732
.LBB0_838:
	v_mov_b64_e32 v[2:3], v[234:235]
	v_mov_b64_e32 v[4:5], v[236:237]
	ds_read_b128 v[24:27], v94 offset:55360
	ds_read_b128 v[28:31], v94 offset:55376
	s_waitcnt vmcnt(0)
	v_lshlrev_b32_e32 v6, 16, v2
	v_and_b32_e32 v7, 0xffff0000, v2
	v_lshlrev_b32_e32 v2, 16, v3
	v_and_b32_e32 v3, 0xffff0000, v3
	v_lshlrev_b32_e32 v32, 16, v4
	v_and_b32_e32 v33, 0xffff0000, v4
	v_lshlrev_b32_e32 v4, 16, v5
	v_and_b32_e32 v5, 0xffff0000, v5
	s_waitcnt lgkmcnt(0)
	v_pk_fma_f32 v[30:31], v[30:31], v[4:5], 0 op_sel_hi:[1,1,0]
	v_pk_fma_f32 v[28:29], v[28:29], v[32:33], 0 op_sel_hi:[1,1,0]
	v_pk_fma_f32 v[26:27], v[26:27], v[2:3], 0 op_sel_hi:[1,1,0]
	v_pk_fma_f32 v[24:25], v[24:25], v[6:7], 0 op_sel_hi:[1,1,0]
	s_or_b64 exec, exec, s[96:97]
	s_and_saveexec_b64 s[96:97], s[90:91]
	s_cbranch_execz .LBB0_734
.LBB0_839:
	v_mov_b64_e32 v[2:3], v[238:239]
	v_mov_b64_e32 v[4:5], v[240:241]
	ds_read_b128 v[32:35], v94 offset:55872
	ds_read_b128 v[36:39], v94 offset:55888
	s_waitcnt vmcnt(0)
	v_lshlrev_b32_e32 v6, 16, v2
	v_and_b32_e32 v7, 0xffff0000, v2
	v_lshlrev_b32_e32 v2, 16, v3
	v_and_b32_e32 v3, 0xffff0000, v3
	v_lshlrev_b32_e32 v40, 16, v4
	v_and_b32_e32 v41, 0xffff0000, v4
	v_lshlrev_b32_e32 v4, 16, v5
	v_and_b32_e32 v5, 0xffff0000, v5
	s_waitcnt lgkmcnt(0)
	v_pk_fma_f32 v[30:31], v[38:39], v[4:5], v[30:31]
	v_pk_fma_f32 v[28:29], v[36:37], v[40:41], v[28:29]
	v_pk_fma_f32 v[26:27], v[34:35], v[2:3], v[26:27]
	v_pk_fma_f32 v[24:25], v[32:33], v[6:7], v[24:25]
	s_or_b64 exec, exec, s[96:97]
	s_and_saveexec_b64 s[96:97], s[92:93]
	s_cbranch_execz .LBB0_735
.LBB0_840:
	v_mov_b64_e32 v[2:3], v[242:243]
	v_mov_b64_e32 v[4:5], v[244:245]
	ds_read_b128 v[32:35], v94 offset:56384
	ds_read_b128 v[36:39], v94 offset:56400
	s_waitcnt vmcnt(0)
	v_lshlrev_b32_e32 v6, 16, v2
	v_and_b32_e32 v7, 0xffff0000, v2
	v_lshlrev_b32_e32 v2, 16, v3
	v_and_b32_e32 v3, 0xffff0000, v3
	v_lshlrev_b32_e32 v40, 16, v4
	v_and_b32_e32 v41, 0xffff0000, v4
	v_lshlrev_b32_e32 v4, 16, v5
	v_and_b32_e32 v5, 0xffff0000, v5
	s_waitcnt lgkmcnt(0)
	v_pk_fma_f32 v[30:31], v[38:39], v[4:5], v[30:31]
	v_pk_fma_f32 v[28:29], v[36:37], v[40:41], v[28:29]
	v_pk_fma_f32 v[26:27], v[34:35], v[2:3], v[26:27]
	v_pk_fma_f32 v[24:25], v[32:33], v[6:7], v[24:25]
	s_or_b64 exec, exec, s[96:97]
	s_and_saveexec_b64 s[96:97], s[94:95]
	s_cbranch_execnz .LBB0_736
	s_branch .LBB0_737

; #define MFMA16(a, b, c) __builtin_amdgcn_mfma_f32_16x16x32_bf16(a, b, c, 0, 0, 0)
; #define MFMA8(a, b, c) __builtin_amdgcn_mfma_f32_16x16x32_fp8_fp8(a, b, c, 0, 0, 0)
; template <bool FP8>
; __device__ __forceinline__ void gemm_tile_256(const u16* __restrict__ A, int lda, const u16* __restrict__ Bt, int ldb,
;                                               int K, char* smem, f32x4 (&acc)[8][4]) {
;     ...
; #pragma unroll
;     for (int kk = 0; kk < 2; ++kk) {
;       const int ch = ((kk * 4 + fq) ^ sw) << 4;
;       bf16x8 bfr[4], af[8];
; #pragma unroll
;       for (int n = 0; n < 4; ++n) bfr[n] = *(const bf16x8*)(smem + brow + n * 2048 + ch);
; #pragma unroll
;       for (int m = 0; m < 8; ++m) af[m] = *(const bf16x8*)(smem + arow + m * 2048 + ch);
;       __builtin_amdgcn_sched_group_barrier(0x100, 12, 0);
;       __builtin_amdgcn_sched_group_barrier(0x008, 32, 0);
; #pragma unroll
;       for (int m = 0; m < 8; ++m)
; #pragma unroll
;         for (int n = 0; n < 4; ++n) {
;           if (FP8) {
;             union { bf16x8 v; long l[2]; } ua, ub;
;             ua.v = af[m]; ub.v = bfr[n];
;             acc[m][n] = MFMA8(ub.l[0], ua.l[0], acc[m][n]);
;             acc[m][n] = MFMA8(ub.l[1], ua.l[1], acc[m][n]);
;           } else {
;             acc[m][n] = MFMA16(bfr[n], af[m], acc[m][n]);
;           }
;         }
;     }
.LBB0_950:
	s_setprio 2
	v_add_u32_e32 v178, v193, v197
	s_waitcnt lgkmcnt(7)
	v_mfma_f32_16x16x32_bf16 v[160:163], v[210:213], v[218:221], v[160:163]
	s_add_u32 s10, s10, 0x80
	s_addc_u32 s11, s11, 0
	s_add_i32 s7, s7, 1
	s_waitcnt lgkmcnt(6)
	v_mfma_f32_16x16x32_bf16 v[96:99], v[210:213], v[222:225], v[96:99]
	s_cmpk_lg_i32 s10, 0x800
	s_waitcnt lgkmcnt(5)
	v_mfma_f32_16x16x32_bf16 v[80:83], v[210:213], v[226:229], v[80:83]
	s_waitcnt lgkmcnt(4)
	v_mfma_f32_16x16x32_bf16 v[64:67], v[210:213], v[230:233], v[64:67]
	s_waitcnt lgkmcnt(3)
	v_mfma_f32_16x16x32_bf16 v[48:51], v[210:213], v[234:237], v[48:51]
	s_waitcnt lgkmcnt(2)
	v_mfma_f32_16x16x32_bf16 v[32:35], v[210:213], v[238:241], v[32:35]
	s_waitcnt lgkmcnt(1)
	v_mfma_f32_16x16x32_bf16 v[16:19], v[210:213], v[242:245], v[16:19]
	s_waitcnt lgkmcnt(0)
	v_mfma_f32_16x16x32_bf16 v[0:3], v[210:213], v[246:249], v[0:3]
	ds_read_b128 v[210:213], v178 offset:38912
	v_mfma_f32_16x16x32_bf16 v[164:167], v[206:209], v[218:221], v[164:167]
	v_mfma_f32_16x16x32_bf16 v[100:103], v[206:209], v[222:225], v[100:103]
	v_mfma_f32_16x16x32_bf16 v[84:87], v[206:209], v[226:229], v[84:87]
	v_mfma_f32_16x16x32_bf16 v[68:71], v[206:209], v[230:233], v[68:71]
	v_mfma_f32_16x16x32_bf16 v[52:55], v[206:209], v[234:237], v[52:55]
	v_mfma_f32_16x16x32_bf16 v[36:39], v[206:209], v[238:241], v[36:39]
	v_mfma_f32_16x16x32_bf16 v[20:23], v[206:209], v[242:245], v[20:23]
	v_mfma_f32_16x16x32_bf16 v[4:7], v[206:209], v[246:249], v[4:7]
	ds_read_b128 v[206:209], v178 offset:36864
	v_mfma_f32_16x16x32_bf16 v[168:171], v[202:205], v[218:221], v[168:171]
	v_mfma_f32_16x16x32_bf16 v[120:123], v[202:205], v[222:225], v[120:123]
	v_mfma_f32_16x16x32_bf16 v[88:91], v[202:205], v[226:229], v[88:91]
	v_mfma_f32_16x16x32_bf16 v[72:75], v[202:205], v[230:233], v[72:75]
	v_mfma_f32_16x16x32_bf16 v[56:59], v[202:205], v[234:237], v[56:59]
	v_mfma_f32_16x16x32_bf16 v[40:43], v[202:205], v[238:241], v[40:43]
	v_mfma_f32_16x16x32_bf16 v[24:27], v[202:205], v[242:245], v[24:27]
	v_mfma_f32_16x16x32_bf16 v[8:11], v[202:205], v[246:249], v[8:11]
	ds_read_b128 v[202:205], v178 offset:34816
	v_mfma_f32_16x16x32_bf16 v[172:175], v[198:201], v[218:221], v[172:175]
	v_mfma_f32_16x16x32_bf16 v[156:159], v[198:201], v[222:225], v[156:159]
	v_mfma_f32_16x16x32_bf16 v[92:95], v[198:201], v[226:229], v[92:95]
	v_mfma_f32_16x16x32_bf16 v[76:79], v[198:201], v[230:233], v[76:79]
	v_mfma_f32_16x16x32_bf16 v[60:63], v[198:201], v[234:237], v[60:63]
	v_mfma_f32_16x16x32_bf16 v[44:47], v[198:201], v[238:241], v[44:47]
	v_mfma_f32_16x16x32_bf16 v[28:31], v[198:201], v[242:245], v[28:31]
	v_mfma_f32_16x16x32_bf16 v[12:15], v[198:201], v[246:249], v[12:15]
	ds_read_b128 v[198:201], v178 offset:32768
	v_add_u32_e32 v178, v194, v197
	ds_read_b128 v[218:221], v178
	ds_read_b128 v[222:225], v178 offset:2048
	ds_read_b128 v[226:229], v178 offset:4096
	ds_read_b128 v[230:233], v178 offset:6144
	ds_read_b128 v[234:237], v178 offset:8192
	ds_read_b128 v[238:241], v178 offset:10240
	ds_read_b128 v[242:245], v178 offset:12288
	ds_read_b128 v[246:249], v178 offset:14336
	s_waitcnt lgkmcnt(7)
	v_mfma_f32_16x16x32_bf16 v[172:175], v[198:201], v[218:221], v[172:175]
	v_mfma_f32_16x16x32_bf16 v[168:171], v[202:205], v[218:221], v[168:171]
	v_mfma_f32_16x16x32_bf16 v[164:167], v[206:209], v[218:221], v[164:167]
	v_mfma_f32_16x16x32_bf16 v[160:163], v[210:213], v[218:221], v[160:163]
	s_waitcnt lgkmcnt(6)
	v_mfma_f32_16x16x32_bf16 v[156:159], v[198:201], v[222:225], v[156:159]
	v_mfma_f32_16x16x32_bf16 v[120:123], v[202:205], v[222:225], v[120:123]
	v_mfma_f32_16x16x32_bf16 v[100:103], v[206:209], v[222:225], v[100:103]
	v_mfma_f32_16x16x32_bf16 v[96:99], v[210:213], v[222:225], v[96:99]
	s_waitcnt lgkmcnt(5)
	v_mfma_f32_16x16x32_bf16 v[92:95], v[198:201], v[226:229], v[92:95]
	v_mfma_f32_16x16x32_bf16 v[88:91], v[202:205], v[226:229], v[88:91]
	v_mfma_f32_16x16x32_bf16 v[84:87], v[206:209], v[226:229], v[84:87]
	v_mfma_f32_16x16x32_bf16 v[80:83], v[210:213], v[226:229], v[80:83]
	s_waitcnt lgkmcnt(4)
	v_mfma_f32_16x16x32_bf16 v[76:79], v[198:201], v[230:233], v[76:79]
	v_mfma_f32_16x16x32_bf16 v[72:75], v[202:205], v[230:233], v[72:75]
	v_mfma_f32_16x16x32_bf16 v[68:71], v[206:209], v[230:233], v[68:71]
	v_mfma_f32_16x16x32_bf16 v[64:67], v[210:213], v[230:233], v[64:67]
	s_waitcnt lgkmcnt(3)
	v_mfma_f32_16x16x32_bf16 v[60:63], v[198:201], v[234:237], v[60:63]
	v_mfma_f32_16x16x32_bf16 v[56:59], v[202:205], v[234:237], v[56:59]
	v_mfma_f32_16x16x32_bf16 v[52:55], v[206:209], v[234:237], v[52:55]
	v_mfma_f32_16x16x32_bf16 v[48:51], v[210:213], v[234:237], v[48:51]
	s_waitcnt lgkmcnt(2)
	v_mfma_f32_16x16x32_bf16 v[44:47], v[198:201], v[238:241], v[44:47]
	v_mfma_f32_16x16x32_bf16 v[40:43], v[202:205], v[238:241], v[40:43]
	v_mfma_f32_16x16x32_bf16 v[36:39], v[206:209], v[238:241], v[36:39]
	v_mfma_f32_16x16x32_bf16 v[32:35], v[210:213], v[238:241], v[32:35]
	s_waitcnt lgkmcnt(1)
	v_mfma_f32_16x16x32_bf16 v[28:31], v[198:201], v[242:245], v[28:31]
	v_mfma_f32_16x16x32_bf16 v[24:27], v[202:205], v[242:245], v[24:27]
	v_mfma_f32_16x16x32_bf16 v[20:23], v[206:209], v[242:245], v[20:23]
	v_mfma_f32_16x16x32_bf16 v[16:19], v[210:213], v[242:245], v[16:19]
	s_waitcnt lgkmcnt(0)
	v_mfma_f32_16x16x32_bf16 v[12:15], v[198:201], v[246:249], v[12:15]
	v_mfma_f32_16x16x32_bf16 v[8:11], v[202:205], v[246:249], v[8:11]
	v_mfma_f32_16x16x32_bf16 v[4:7], v[206:209], v[246:249], v[4:7]
	v_mfma_f32_16x16x32_bf16 v[0:3], v[210:213], v[246:249], v[0:3]
	s_cbranch_scc0 .LBB0_953
; template <bool FP8>
; __device__ __forceinline__ void gemm_tile_256(const u16* __restrict__ A, int lda, const u16* __restrict__ Bt, int ldb,
;                                               int K, char* smem, f32x4 (&acc)[8][4]) {
;     ...
;   for (int kt = 0; kt < nk; ++kt) {
;     __syncthreads();
; #pragma unroll
;     for (int q = 0; q < 8; ++q) *(u32x4*)(smem + wofs + q * 4096) = ra[q];
; #pragma unroll
;     for (int q = 0; q < 4; ++q) *(u32x4*)(smem + 32768 + wofs + q * 4096) = rb[q];
;     __syncthreads();
;     if (kt + 1 < nk) {
;       const int k0 = (kt + 1) << 6;
; #pragma unroll
;       for (int q = 0; q < 8; ++q) ra[q] = *(const u32x4*)(ag + (size_t)q * 32 * lda + k0);
; #pragma unroll
;       for (int q = 0; q < 4; ++q) rb[q] = *(const u32x4*)(bg + (size_t)q * 32 * ldb + k0);
;     }
.LBB0_951:
	s_cmp_gt_u32 s7, 14
	s_setprio 0
	s_barrier
	s_waitcnt vmcnt(0)
	ds_write_b128 v195, v[104:107]
	ds_write_b128 v195, v[108:111] offset:4096
	ds_write_b128 v195, v[128:131] offset:8192
	ds_write_b128 v195, v[112:115] offset:12288
	ds_write_b128 v195, v[132:135] offset:16384
	ds_write_b128 v195, v[116:119] offset:20480
	ds_write_b128 v195, v[136:139] offset:24576
	ds_write_b128 v195, v[124:127] offset:28672
	ds_write_b128 v195, v[152:155] offset:32768
	ds_write_b128 v195, v[140:143] offset:36864
	ds_write_b128 v195, v[148:151] offset:40960
	ds_write_b128 v195, v[144:147] offset:45056
	s_waitcnt lgkmcnt(0)
	s_barrier
	v_add_u32_e32 v178, v193, v196
	ds_read_b128 v[198:201], v178 offset:32768
	ds_read_b128 v[202:205], v178 offset:34816
	ds_read_b128 v[206:209], v178 offset:36864
	ds_read_b128 v[210:213], v178 offset:38912
	v_add_u32_e32 v178, v194, v196
	ds_read_b128 v[218:221], v178
	ds_read_b128 v[222:225], v178 offset:2048
	ds_read_b128 v[226:229], v178 offset:4096
	ds_read_b128 v[230:233], v178 offset:6144
	ds_read_b128 v[234:237], v178 offset:8192
	ds_read_b128 v[238:241], v178 offset:10240
	ds_read_b128 v[242:245], v178 offset:12288
	ds_read_b128 v[246:249], v178 offset:14336
	s_cbranch_scc1 .LBB0_950
	v_lshl_add_u64 v[124:125], v[180:181], 0, s[10:11]
	v_add_co_u32_e32 v108, vcc, 0x10000, v124
	v_lshl_add_u64 v[144:145], v[182:183], 0, s[10:11]
	s_nop 0
	v_addc_co_u32_e32 v109, vcc, 0, v125, vcc
	v_add_co_u32_e32 v112, vcc, 0x20000, v124
	global_load_dwordx4 v[104:107], v[124:125], off offset:128
	s_nop 0
	global_load_dwordx4 v[108:111], v[108:109], off offset:128
	v_addc_co_u32_e32 v113, vcc, 0, v125, vcc
	v_add_co_u32_e32 v114, vcc, 0x30000, v124
	s_nop 1
	v_addc_co_u32_e32 v115, vcc, 0, v125, vcc
	v_add_co_u32_e32 v116, vcc, 0x40000, v124
	global_load_dwordx4 v[128:131], v[112:113], off offset:128
	s_nop 0
	global_load_dwordx4 v[112:115], v[114:115], off offset:128
	v_addc_co_u32_e32 v117, vcc, 0, v125, vcc
	v_add_co_u32_e32 v118, vcc, 0x50000, v124
	s_nop 1
	v_addc_co_u32_e32 v119, vcc, 0, v125, vcc
	v_add_co_u32_e32 v126, vcc, 0x60000, v124
	global_load_dwordx4 v[132:135], v[116:117], off offset:128
	s_nop 0
	global_load_dwordx4 v[116:119], v[118:119], off offset:128
	v_addc_co_u32_e32 v127, vcc, 0, v125, vcc
	v_add_co_u32_e32 v124, vcc, 0x70000, v124
	s_nop 1
	v_addc_co_u32_e32 v125, vcc, 0, v125, vcc
	v_add_co_u32_e32 v140, vcc, 0x10000, v144
	global_load_dwordx4 v[136:139], v[126:127], off offset:128
	s_nop 0
	global_load_dwordx4 v[124:127], v[124:125], off offset:128
	v_addc_co_u32_e32 v141, vcc, 0, v145, vcc
	v_add_co_u32_e32 v146, vcc, 0x20000, v144
	global_load_dwordx4 v[152:155], v[144:145], off offset:128
	s_nop 0
	global_load_dwordx4 v[140:143], v[140:141], off offset:128
	v_addc_co_u32_e32 v147, vcc, 0, v145, vcc
	v_add_co_u32_e32 v144, vcc, 0x30000, v144
	s_nop 1
	v_addc_co_u32_e32 v145, vcc, 0, v145, vcc
	global_load_dwordx4 v[148:151], v[146:147], off offset:128
	s_nop 0
	global_load_dwordx4 v[144:147], v[144:145], off offset:128
	s_branch .LBB0_950

; #define MFMA16(a, b, c) __builtin_amdgcn_mfma_f32_16x16x32_bf16(a, b, c, 0, 0, 0)
; #define MFMA8(a, b, c) __builtin_amdgcn_mfma_f32_16x16x32_fp8_fp8(a, b, c, 0, 0, 0)
; template <bool FP8>
; __device__ __forceinline__ void gemm_tile_256(const u16* __restrict__ A, int lda, const u16* __restrict__ Bt, int ldb,
;                                               int K, char* smem, f32x4 (&acc)[8][4]) {
;     ...
; #pragma unroll
;     for (int kk = 0; kk < 2; ++kk) {
;       const int ch = ((kk * 4 + fq) ^ sw) << 4;
;       bf16x8 bfr[4], af[8];
; #pragma unroll
;       for (int n = 0; n < 4; ++n) bfr[n] = *(const bf16x8*)(smem + brow + n * 2048 + ch);
; #pragma unroll
;       for (int m = 0; m < 8; ++m) af[m] = *(const bf16x8*)(smem + arow + m * 2048 + ch);
;       __builtin_amdgcn_sched_group_barrier(0x100, 12, 0);
;       __builtin_amdgcn_sched_group_barrier(0x008, 32, 0);
; #pragma unroll
;       for (int m = 0; m < 8; ++m)
; #pragma unroll
;         for (int n = 0; n < 4; ++n) {
;           if (FP8) {
;             union { bf16x8 v; long l[2]; } ua, ub;
;             ua.v = af[m]; ub.v = bfr[n];
;             acc[m][n] = MFMA8(ub.l[0], ua.l[0], acc[m][n]);
;             acc[m][n] = MFMA8(ub.l[1], ua.l[1], acc[m][n]);
;           } else {
;             acc[m][n] = MFMA16(bfr[n], af[m], acc[m][n]);
;           }
;         }
;     }
.LBB0_1032:
	s_setprio 2
	v_add_u32_e32 v178, v193, v197
	s_waitcnt lgkmcnt(7)
	v_mfma_f32_16x16x32_bf16 v[40:43], v[210:213], v[218:221], v[40:43]
	s_add_u32 s8, s8, 0x80
	s_addc_u32 s9, s9, 0
	s_add_i32 s0, s0, 1
	s_waitcnt lgkmcnt(6)
	v_mfma_f32_16x16x32_bf16 v[32:35], v[210:213], v[222:225], v[32:35]
	s_cmpk_lg_i32 s8, 0x1000
	s_waitcnt lgkmcnt(5)
	v_mfma_f32_16x16x32_bf16 v[24:27], v[210:213], v[226:229], v[24:27]
	s_waitcnt lgkmcnt(4)
	v_mfma_f32_16x16x32_bf16 v[16:19], v[210:213], v[230:233], v[16:19]
	s_waitcnt lgkmcnt(3)
	v_mfma_f32_16x16x32_bf16 v[12:15], v[210:213], v[234:237], v[12:15]
	s_waitcnt lgkmcnt(2)
	v_mfma_f32_16x16x32_bf16 v[8:11], v[210:213], v[238:241], v[8:11]
	s_waitcnt lgkmcnt(1)
	v_mfma_f32_16x16x32_bf16 v[4:7], v[210:213], v[242:245], v[4:7]
	s_waitcnt lgkmcnt(0)
	v_mfma_f32_16x16x32_bf16 v[0:3], v[210:213], v[246:249], v[0:3]
	ds_read_b128 v[210:213], v178 offset:38912
	v_mfma_f32_16x16x32_bf16 v[72:75], v[206:209], v[218:221], v[72:75]
	v_mfma_f32_16x16x32_bf16 v[64:67], v[206:209], v[222:225], v[64:67]
	v_mfma_f32_16x16x32_bf16 v[56:59], v[206:209], v[226:229], v[56:59]
	v_mfma_f32_16x16x32_bf16 v[48:51], v[206:209], v[230:233], v[48:51]
	v_mfma_f32_16x16x32_bf16 v[44:47], v[206:209], v[234:237], v[44:47]
	v_mfma_f32_16x16x32_bf16 v[36:39], v[206:209], v[238:241], v[36:39]
	v_mfma_f32_16x16x32_bf16 v[28:31], v[206:209], v[242:245], v[28:31]
	v_mfma_f32_16x16x32_bf16 v[20:23], v[206:209], v[246:249], v[20:23]
	ds_read_b128 v[206:209], v178 offset:36864
	v_mfma_f32_16x16x32_bf16 v[152:155], v[202:205], v[218:221], v[152:155]
	v_mfma_f32_16x16x32_bf16 v[140:143], v[202:205], v[222:225], v[140:143]
	v_mfma_f32_16x16x32_bf16 v[88:91], v[202:205], v[226:229], v[88:91]
	v_mfma_f32_16x16x32_bf16 v[80:83], v[202:205], v[230:233], v[80:83]
	v_mfma_f32_16x16x32_bf16 v[76:79], v[202:205], v[234:237], v[76:79]
	v_mfma_f32_16x16x32_bf16 v[68:71], v[202:205], v[238:241], v[68:71]
	v_mfma_f32_16x16x32_bf16 v[60:63], v[202:205], v[242:245], v[60:63]
	v_mfma_f32_16x16x32_bf16 v[52:55], v[202:205], v[246:249], v[52:55]
	ds_read_b128 v[202:205], v178 offset:34816
	v_mfma_f32_16x16x32_bf16 v[172:175], v[198:201], v[218:221], v[172:175]
	v_mfma_f32_16x16x32_bf16 v[168:171], v[198:201], v[222:225], v[168:171]
	v_mfma_f32_16x16x32_bf16 v[164:167], v[198:201], v[226:229], v[164:167]
	v_mfma_f32_16x16x32_bf16 v[160:163], v[198:201], v[230:233], v[160:163]
	v_mfma_f32_16x16x32_bf16 v[156:159], v[198:201], v[234:237], v[156:159]
	v_mfma_f32_16x16x32_bf16 v[144:147], v[198:201], v[238:241], v[144:147]
	v_mfma_f32_16x16x32_bf16 v[100:103], v[198:201], v[242:245], v[100:103]
	v_mfma_f32_16x16x32_bf16 v[84:87], v[198:201], v[246:249], v[84:87]
	ds_read_b128 v[198:201], v178 offset:32768
	v_add_u32_e32 v178, v194, v197
	ds_read_b128 v[218:221], v178
	ds_read_b128 v[222:225], v178 offset:2048
	ds_read_b128 v[226:229], v178 offset:4096
	ds_read_b128 v[230:233], v178 offset:6144
	ds_read_b128 v[234:237], v178 offset:8192
	ds_read_b128 v[238:241], v178 offset:10240
	ds_read_b128 v[242:245], v178 offset:12288
	ds_read_b128 v[246:249], v178 offset:14336
	s_waitcnt lgkmcnt(7)
	v_mfma_f32_16x16x32_bf16 v[172:175], v[198:201], v[218:221], v[172:175]
	v_mfma_f32_16x16x32_bf16 v[152:155], v[202:205], v[218:221], v[152:155]
	v_mfma_f32_16x16x32_bf16 v[72:75], v[206:209], v[218:221], v[72:75]
	v_mfma_f32_16x16x32_bf16 v[40:43], v[210:213], v[218:221], v[40:43]
	s_waitcnt lgkmcnt(6)
	v_mfma_f32_16x16x32_bf16 v[168:171], v[198:201], v[222:225], v[168:171]
	v_mfma_f32_16x16x32_bf16 v[140:143], v[202:205], v[222:225], v[140:143]
	v_mfma_f32_16x16x32_bf16 v[64:67], v[206:209], v[222:225], v[64:67]
	v_mfma_f32_16x16x32_bf16 v[32:35], v[210:213], v[222:225], v[32:35]
	s_waitcnt lgkmcnt(5)
	v_mfma_f32_16x16x32_bf16 v[164:167], v[198:201], v[226:229], v[164:167]
	v_mfma_f32_16x16x32_bf16 v[88:91], v[202:205], v[226:229], v[88:91]
	v_mfma_f32_16x16x32_bf16 v[56:59], v[206:209], v[226:229], v[56:59]
	v_mfma_f32_16x16x32_bf16 v[24:27], v[210:213], v[226:229], v[24:27]
	s_waitcnt lgkmcnt(4)
	v_mfma_f32_16x16x32_bf16 v[160:163], v[198:201], v[230:233], v[160:163]
	v_mfma_f32_16x16x32_bf16 v[80:83], v[202:205], v[230:233], v[80:83]
	v_mfma_f32_16x16x32_bf16 v[48:51], v[206:209], v[230:233], v[48:51]
	v_mfma_f32_16x16x32_bf16 v[16:19], v[210:213], v[230:233], v[16:19]
	s_waitcnt lgkmcnt(3)
	v_mfma_f32_16x16x32_bf16 v[156:159], v[198:201], v[234:237], v[156:159]
	v_mfma_f32_16x16x32_bf16 v[76:79], v[202:205], v[234:237], v[76:79]
	v_mfma_f32_16x16x32_bf16 v[44:47], v[206:209], v[234:237], v[44:47]
	v_mfma_f32_16x16x32_bf16 v[12:15], v[210:213], v[234:237], v[12:15]
	s_waitcnt lgkmcnt(2)
	v_mfma_f32_16x16x32_bf16 v[144:147], v[198:201], v[238:241], v[144:147]
	v_mfma_f32_16x16x32_bf16 v[68:71], v[202:205], v[238:241], v[68:71]
	v_mfma_f32_16x16x32_bf16 v[36:39], v[206:209], v[238:241], v[36:39]
	v_mfma_f32_16x16x32_bf16 v[8:11], v[210:213], v[238:241], v[8:11]
	s_waitcnt lgkmcnt(1)
	v_mfma_f32_16x16x32_bf16 v[100:103], v[198:201], v[242:245], v[100:103]
	v_mfma_f32_16x16x32_bf16 v[60:63], v[202:205], v[242:245], v[60:63]
	v_mfma_f32_16x16x32_bf16 v[28:31], v[206:209], v[242:245], v[28:31]
	v_mfma_f32_16x16x32_bf16 v[4:7], v[210:213], v[242:245], v[4:7]
	s_waitcnt lgkmcnt(0)
	v_mfma_f32_16x16x32_bf16 v[84:87], v[198:201], v[246:249], v[84:87]
	v_mfma_f32_16x16x32_bf16 v[52:55], v[202:205], v[246:249], v[52:55]
	v_mfma_f32_16x16x32_bf16 v[20:23], v[206:209], v[246:249], v[20:23]
	v_mfma_f32_16x16x32_bf16 v[0:3], v[210:213], v[246:249], v[0:3]
	s_cbranch_scc0 .LBB0_1030
; template <bool FP8>
; __device__ __forceinline__ void gemm_tile_256(const u16* __restrict__ A, int lda, const u16* __restrict__ Bt, int ldb,
;                                               int K, char* smem, f32x4 (&acc)[8][4]) {
;     ...
;   for (int kt = 0; kt < nk; ++kt) {
;     __syncthreads();
; #pragma unroll
;     for (int q = 0; q < 8; ++q) *(u32x4*)(smem + wofs + q * 4096) = ra[q];
; #pragma unroll
;     for (int q = 0; q < 4; ++q) *(u32x4*)(smem + 32768 + wofs + q * 4096) = rb[q];
;     __syncthreads();
;     if (kt + 1 < nk) {
;       const int k0 = (kt + 1) << 6;
; #pragma unroll
;       for (int q = 0; q < 8; ++q) ra[q] = *(const u32x4*)(ag + (size_t)q * 32 * lda + k0);
; #pragma unroll
;       for (int q = 0; q < 4; ++q) rb[q] = *(const u32x4*)(bg + (size_t)q * 32 * ldb + k0);
;     }
.LBB0_1033:
	s_cmp_gt_u32 s0, 30
	s_setprio 0
	s_barrier
	s_waitcnt vmcnt(0)
	ds_write_b128 v195, v[92:95]
	ds_write_b128 v195, v[96:99] offset:4096
	ds_write_b128 v195, v[116:119] offset:8192
	ds_write_b128 v195, v[104:107] offset:12288
	ds_write_b128 v195, v[120:123] offset:16384
	ds_write_b128 v195, v[108:111] offset:20480
	ds_write_b128 v195, v[124:127] offset:24576
	ds_write_b128 v195, v[112:115] offset:28672
	ds_write_b128 v195, v[148:151] offset:32768
	ds_write_b128 v195, v[128:131] offset:36864
	ds_write_b128 v195, v[136:139] offset:40960
	ds_write_b128 v195, v[132:135] offset:45056
	s_waitcnt lgkmcnt(0)
	s_barrier
	v_add_u32_e32 v178, v193, v196
	ds_read_b128 v[198:201], v178 offset:32768
	ds_read_b128 v[202:205], v178 offset:34816
	ds_read_b128 v[206:209], v178 offset:36864
	ds_read_b128 v[210:213], v178 offset:38912
	v_add_u32_e32 v178, v194, v196
	ds_read_b128 v[218:221], v178
	ds_read_b128 v[222:225], v178 offset:2048
	ds_read_b128 v[226:229], v178 offset:4096
	ds_read_b128 v[230:233], v178 offset:6144
	ds_read_b128 v[234:237], v178 offset:8192
	ds_read_b128 v[238:241], v178 offset:10240
	ds_read_b128 v[242:245], v178 offset:12288
	ds_read_b128 v[246:249], v178 offset:14336
	s_cbranch_scc1 .LBB0_1032
	v_lshl_add_u64 v[112:113], v[180:181], 0, s[8:9]
	v_add_co_u32_e32 v92, vcc, 0x1cc00000, v112
	v_lshl_add_u64 v[132:133], v[182:183], 0, s[8:9]
	s_nop 0
	v_addc_co_u32_e32 v93, vcc, 0, v113, vcc
	v_add_co_u32_e32 v96, vcc, 0x1cc20000, v112
	s_nop 1
	v_addc_co_u32_e32 v97, vcc, 0, v113, vcc
	v_add_co_u32_e32 v104, vcc, 0x1cc40000, v112
	global_load_dwordx4 v[92:95], v[92:93], off offset:128
	s_nop 0
	global_load_dwordx4 v[96:99], v[96:97], off offset:128
	v_addc_co_u32_e32 v105, vcc, 0, v113, vcc
	v_add_co_u32_e32 v106, vcc, 0x1cc60000, v112
	s_nop 1
	v_addc_co_u32_e32 v107, vcc, 0, v113, vcc
	v_add_co_u32_e32 v108, vcc, 0x1cc80000, v112
	global_load_dwordx4 v[116:119], v[104:105], off offset:128
	s_nop 0
	global_load_dwordx4 v[104:107], v[106:107], off offset:128
	v_addc_co_u32_e32 v109, vcc, 0, v113, vcc
	v_add_co_u32_e32 v110, vcc, 0x1cca0000, v112
	s_nop 1
	v_addc_co_u32_e32 v111, vcc, 0, v113, vcc
	v_add_co_u32_e32 v114, vcc, 0x1ccc0000, v112
	global_load_dwordx4 v[120:123], v[108:109], off offset:128
	s_nop 0
	global_load_dwordx4 v[108:111], v[110:111], off offset:128
	v_addc_co_u32_e32 v115, vcc, 0, v113, vcc
	v_add_co_u32_e32 v112, vcc, 0x1cce0000, v112
	s_nop 1
	v_addc_co_u32_e32 v113, vcc, 0, v113, vcc
	v_add_co_u32_e32 v128, vcc, 0x3880000, v132
	global_load_dwordx4 v[124:127], v[114:115], off offset:128
	s_nop 0
	global_load_dwordx4 v[112:115], v[112:113], off offset:128
	v_addc_co_u32_e32 v129, vcc, 0, v133, vcc
	v_add_co_u32_e32 v130, vcc, 0x38a0000, v132
	s_nop 1
	v_addc_co_u32_e32 v131, vcc, 0, v133, vcc
	v_add_co_u32_e32 v134, vcc, 0x38c0000, v132
	global_load_dwordx4 v[148:151], v[128:129], off offset:128
	s_nop 0
	global_load_dwordx4 v[128:131], v[130:131], off offset:128
	v_addc_co_u32_e32 v135, vcc, 0, v133, vcc
	v_add_co_u32_e32 v132, vcc, 0x38e0000, v132
	s_nop 1
	v_addc_co_u32_e32 v133, vcc, 0, v133, vcc
	global_load_dwordx4 v[136:139], v[134:135], off offset:128
	s_nop 0
	global_load_dwordx4 v[132:135], v[132:133], off offset:128
	s_branch .LBB0_1032

; #define MFMA16(a, b, c) __builtin_amdgcn_mfma_f32_16x16x32_bf16(a, b, c, 0, 0, 0)
; #define MFMA8(a, b, c) __builtin_amdgcn_mfma_f32_16x16x32_fp8_fp8(a, b, c, 0, 0, 0)
; template <bool FP8>
; __device__ __forceinline__ void gemm_tile_256(const u16* __restrict__ A, int lda, const u16* __restrict__ Bt, int ldb,
;                                               int K, char* smem, f32x4 (&acc)[8][4]) {
;     ...
; #pragma unroll
;     for (int kk = 0; kk < 2; ++kk) {
;       const int ch = ((kk * 4 + fq) ^ sw) << 4;
;       bf16x8 bfr[4], af[8];
; #pragma unroll
;       for (int n = 0; n < 4; ++n) bfr[n] = *(const bf16x8*)(smem + brow + n * 2048 + ch);
; #pragma unroll
;       for (int m = 0; m < 8; ++m) af[m] = *(const bf16x8*)(smem + arow + m * 2048 + ch);
;       __builtin_amdgcn_sched_group_barrier(0x100, 12, 0);
;       __builtin_amdgcn_sched_group_barrier(0x008, 32, 0);
; #pragma unroll
;       for (int m = 0; m < 8; ++m)
; #pragma unroll
;         for (int n = 0; n < 4; ++n) {
;           if (FP8) {
;             union { bf16x8 v; long l[2]; } ua, ub;
;             ua.v = af[m]; ub.v = bfr[n];
;             acc[m][n] = MFMA8(ub.l[0], ua.l[0], acc[m][n]);
;             acc[m][n] = MFMA8(ub.l[1], ua.l[1], acc[m][n]);
;           } else {
;             acc[m][n] = MFMA16(bfr[n], af[m], acc[m][n]);
;           }
;         }
;     }
.LBB0_1072:
	s_setprio 2
	v_add_u32_e32 v178, v193, v197
	s_waitcnt lgkmcnt(7)
	v_mfma_f32_16x16x32_bf16 v[160:163], v[210:213], v[218:221], v[160:163]
	s_add_u32 s18, s18, 0x80
	s_addc_u32 s19, s19, 0
	s_add_i32 s0, s0, 1
	s_waitcnt lgkmcnt(6)
	v_mfma_f32_16x16x32_bf16 v[144:147], v[210:213], v[222:225], v[144:147]
	s_cmpk_lg_i32 s18, 0x1000
	s_waitcnt lgkmcnt(5)
	v_mfma_f32_16x16x32_bf16 v[128:131], v[210:213], v[226:229], v[128:131]
	s_waitcnt lgkmcnt(4)
	v_mfma_f32_16x16x32_bf16 v[112:115], v[210:213], v[230:233], v[112:115]
	s_waitcnt lgkmcnt(3)
	v_mfma_f32_16x16x32_bf16 v[96:99], v[210:213], v[234:237], v[96:99]
	s_waitcnt lgkmcnt(2)
	v_mfma_f32_16x16x32_bf16 v[80:83], v[210:213], v[238:241], v[80:83]
	s_waitcnt lgkmcnt(1)
	v_mfma_f32_16x16x32_bf16 v[64:67], v[210:213], v[242:245], v[64:67]
	s_waitcnt lgkmcnt(0)
	v_mfma_f32_16x16x32_bf16 v[48:51], v[210:213], v[246:249], v[48:51]
	ds_read_b128 v[210:213], v178 offset:38912
	v_mfma_f32_16x16x32_bf16 v[164:167], v[206:209], v[218:221], v[164:167]
	v_mfma_f32_16x16x32_bf16 v[148:151], v[206:209], v[222:225], v[148:151]
	v_mfma_f32_16x16x32_bf16 v[132:135], v[206:209], v[226:229], v[132:135]
	v_mfma_f32_16x16x32_bf16 v[116:119], v[206:209], v[230:233], v[116:119]
	v_mfma_f32_16x16x32_bf16 v[100:103], v[206:209], v[234:237], v[100:103]
	v_mfma_f32_16x16x32_bf16 v[84:87], v[206:209], v[238:241], v[84:87]
	v_mfma_f32_16x16x32_bf16 v[68:71], v[206:209], v[242:245], v[68:71]
	v_mfma_f32_16x16x32_bf16 v[56:59], v[206:209], v[246:249], v[56:59]
	ds_read_b128 v[206:209], v178 offset:36864
	v_mfma_f32_16x16x32_bf16 v[168:171], v[202:205], v[218:221], v[168:171]
	v_mfma_f32_16x16x32_bf16 v[152:155], v[202:205], v[222:225], v[152:155]
	v_mfma_f32_16x16x32_bf16 v[136:139], v[202:205], v[226:229], v[136:139]
	v_mfma_f32_16x16x32_bf16 v[120:123], v[202:205], v[230:233], v[120:123]
	v_mfma_f32_16x16x32_bf16 v[104:107], v[202:205], v[234:237], v[104:107]
	v_mfma_f32_16x16x32_bf16 v[88:91], v[202:205], v[238:241], v[88:91]
	v_mfma_f32_16x16x32_bf16 v[72:75], v[202:205], v[242:245], v[72:75]
	v_mfma_f32_16x16x32_bf16 v[52:55], v[202:205], v[246:249], v[52:55]
	ds_read_b128 v[202:205], v178 offset:34816
	v_mfma_f32_16x16x32_bf16 v[172:175], v[198:201], v[218:221], v[172:175]
	v_mfma_f32_16x16x32_bf16 v[156:159], v[198:201], v[222:225], v[156:159]
	v_mfma_f32_16x16x32_bf16 v[140:143], v[198:201], v[226:229], v[140:143]
	v_mfma_f32_16x16x32_bf16 v[124:127], v[198:201], v[230:233], v[124:127]
	v_mfma_f32_16x16x32_bf16 v[108:111], v[198:201], v[234:237], v[108:111]
	v_mfma_f32_16x16x32_bf16 v[92:95], v[198:201], v[238:241], v[92:95]
	v_mfma_f32_16x16x32_bf16 v[76:79], v[198:201], v[242:245], v[76:79]
	v_mfma_f32_16x16x32_bf16 v[60:63], v[198:201], v[246:249], v[60:63]
	ds_read_b128 v[198:201], v178 offset:32768
	v_add_u32_e32 v178, v194, v197
	ds_read_b128 v[218:221], v178
	ds_read_b128 v[222:225], v178 offset:2048
	ds_read_b128 v[226:229], v178 offset:4096
	ds_read_b128 v[230:233], v178 offset:6144
	ds_read_b128 v[234:237], v178 offset:8192
	ds_read_b128 v[238:241], v178 offset:10240
	ds_read_b128 v[242:245], v178 offset:12288
	ds_read_b128 v[246:249], v178 offset:14336
	s_waitcnt lgkmcnt(7)
	v_mfma_f32_16x16x32_bf16 v[172:175], v[198:201], v[218:221], v[172:175]
	v_mfma_f32_16x16x32_bf16 v[168:171], v[202:205], v[218:221], v[168:171]
	v_mfma_f32_16x16x32_bf16 v[164:167], v[206:209], v[218:221], v[164:167]
	v_mfma_f32_16x16x32_bf16 v[160:163], v[210:213], v[218:221], v[160:163]
	s_waitcnt lgkmcnt(6)
	v_mfma_f32_16x16x32_bf16 v[156:159], v[198:201], v[222:225], v[156:159]
	v_mfma_f32_16x16x32_bf16 v[152:155], v[202:205], v[222:225], v[152:155]
	v_mfma_f32_16x16x32_bf16 v[148:151], v[206:209], v[222:225], v[148:151]
	v_mfma_f32_16x16x32_bf16 v[144:147], v[210:213], v[222:225], v[144:147]
	s_waitcnt lgkmcnt(5)
	v_mfma_f32_16x16x32_bf16 v[140:143], v[198:201], v[226:229], v[140:143]
	v_mfma_f32_16x16x32_bf16 v[136:139], v[202:205], v[226:229], v[136:139]
	v_mfma_f32_16x16x32_bf16 v[132:135], v[206:209], v[226:229], v[132:135]
	v_mfma_f32_16x16x32_bf16 v[128:131], v[210:213], v[226:229], v[128:131]
	s_waitcnt lgkmcnt(4)
	v_mfma_f32_16x16x32_bf16 v[124:127], v[198:201], v[230:233], v[124:127]
	v_mfma_f32_16x16x32_bf16 v[120:123], v[202:205], v[230:233], v[120:123]
	v_mfma_f32_16x16x32_bf16 v[116:119], v[206:209], v[230:233], v[116:119]
	v_mfma_f32_16x16x32_bf16 v[112:115], v[210:213], v[230:233], v[112:115]
	s_waitcnt lgkmcnt(3)
	v_mfma_f32_16x16x32_bf16 v[108:111], v[198:201], v[234:237], v[108:111]
	v_mfma_f32_16x16x32_bf16 v[104:107], v[202:205], v[234:237], v[104:107]
	v_mfma_f32_16x16x32_bf16 v[100:103], v[206:209], v[234:237], v[100:103]
	v_mfma_f32_16x16x32_bf16 v[96:99], v[210:213], v[234:237], v[96:99]
	s_waitcnt lgkmcnt(2)
	v_mfma_f32_16x16x32_bf16 v[92:95], v[198:201], v[238:241], v[92:95]
	v_mfma_f32_16x16x32_bf16 v[88:91], v[202:205], v[238:241], v[88:91]
	v_mfma_f32_16x16x32_bf16 v[84:87], v[206:209], v[238:241], v[84:87]
	v_mfma_f32_16x16x32_bf16 v[80:83], v[210:213], v[238:241], v[80:83]
	s_waitcnt lgkmcnt(1)
	v_mfma_f32_16x16x32_bf16 v[76:79], v[198:201], v[242:245], v[76:79]
	v_mfma_f32_16x16x32_bf16 v[72:75], v[202:205], v[242:245], v[72:75]
	v_mfma_f32_16x16x32_bf16 v[68:71], v[206:209], v[242:245], v[68:71]
	v_mfma_f32_16x16x32_bf16 v[64:67], v[210:213], v[242:245], v[64:67]
	s_waitcnt lgkmcnt(0)
	v_mfma_f32_16x16x32_bf16 v[60:63], v[198:201], v[246:249], v[60:63]
	v_mfma_f32_16x16x32_bf16 v[52:55], v[202:205], v[246:249], v[52:55]
	v_mfma_f32_16x16x32_bf16 v[56:59], v[206:209], v[246:249], v[56:59]
	v_mfma_f32_16x16x32_bf16 v[48:51], v[210:213], v[246:249], v[48:51]
	s_cbranch_scc0 .LBB0_1070
; template <bool FP8>
; __device__ __forceinline__ void gemm_tile_256(const u16* __restrict__ A, int lda, const u16* __restrict__ Bt, int ldb,
;                                               int K, char* smem, f32x4 (&acc)[8][4]) {
;     ...
;   for (int kt = 0; kt < nk; ++kt) {
;     __syncthreads();
; #pragma unroll
;     for (int q = 0; q < 8; ++q) *(u32x4*)(smem + wofs + q * 4096) = ra[q];
; #pragma unroll
;     for (int q = 0; q < 4; ++q) *(u32x4*)(smem + 32768 + wofs + q * 4096) = rb[q];
;     __syncthreads();
;     if (kt + 1 < nk) {
;       const int k0 = (kt + 1) << 6;
; #pragma unroll
;       for (int q = 0; q < 8; ++q) ra[q] = *(const u32x4*)(ag + (size_t)q * 32 * lda + k0);
; #pragma unroll
;       for (int q = 0; q < 4; ++q) rb[q] = *(const u32x4*)(bg + (size_t)q * 32 * ldb + k0);
;     }
.LBB0_1073:
	s_cmp_gt_u32 s0, 30
	s_setprio 0
	s_barrier
	s_waitcnt vmcnt(0)
	ds_write_b128 v195, v[0:3]
	ds_write_b128 v195, v[4:7] offset:4096
	ds_write_b128 v195, v[20:23] offset:8192
	ds_write_b128 v195, v[8:11] offset:12288
	ds_write_b128 v195, v[24:27] offset:16384
	ds_write_b128 v195, v[12:15] offset:20480
	ds_write_b128 v195, v[28:31] offset:24576
	ds_write_b128 v195, v[16:19] offset:28672
	ds_write_b128 v195, v[44:47] offset:32768
	ds_write_b128 v195, v[32:35] offset:36864
	ds_write_b128 v195, v[40:43] offset:40960
	ds_write_b128 v195, v[36:39] offset:45056
	s_waitcnt lgkmcnt(0)
	s_barrier
	v_add_u32_e32 v178, v193, v196
	ds_read_b128 v[198:201], v178 offset:32768
	ds_read_b128 v[202:205], v178 offset:34816
	ds_read_b128 v[206:209], v178 offset:36864
	ds_read_b128 v[210:213], v178 offset:38912
	v_add_u32_e32 v178, v194, v196
	ds_read_b128 v[218:221], v178
	ds_read_b128 v[222:225], v178 offset:2048
	ds_read_b128 v[226:229], v178 offset:4096
	ds_read_b128 v[230:233], v178 offset:6144
	ds_read_b128 v[234:237], v178 offset:8192
	ds_read_b128 v[238:241], v178 offset:10240
	ds_read_b128 v[242:245], v178 offset:12288
	ds_read_b128 v[246:249], v178 offset:14336
	s_cbranch_scc1 .LBB0_1072
	v_lshl_add_u64 v[16:17], v[180:181], 0, s[18:19]
	v_add_co_u32_e32 v0, vcc, 0x4c00000, v16
	v_lshl_add_u64 v[36:37], v[182:183], 0, s[18:19]
	s_nop 0
	v_addc_co_u32_e32 v1, vcc, 0, v17, vcc
	v_add_co_u32_e32 v4, vcc, 0x4c20000, v16
	s_nop 1
	v_addc_co_u32_e32 v5, vcc, 0, v17, vcc
	v_add_co_u32_e32 v8, vcc, 0x4c40000, v16
	global_load_dwordx4 v[0:3], v[0:1], off offset:128
	s_nop 0
	global_load_dwordx4 v[4:7], v[4:5], off offset:128
	v_addc_co_u32_e32 v9, vcc, 0, v17, vcc
	v_add_co_u32_e32 v10, vcc, 0x4c60000, v16
	s_nop 1
	v_addc_co_u32_e32 v11, vcc, 0, v17, vcc
	v_add_co_u32_e32 v12, vcc, 0x4c80000, v16
	global_load_dwordx4 v[20:23], v[8:9], off offset:128
	s_nop 0
	global_load_dwordx4 v[8:11], v[10:11], off offset:128
	v_addc_co_u32_e32 v13, vcc, 0, v17, vcc
	v_add_co_u32_e32 v14, vcc, 0x4ca0000, v16
	s_nop 1
	v_addc_co_u32_e32 v15, vcc, 0, v17, vcc
	v_add_co_u32_e32 v18, vcc, 0x4cc0000, v16
	global_load_dwordx4 v[24:27], v[12:13], off offset:128
	s_nop 0
	global_load_dwordx4 v[12:15], v[14:15], off offset:128
	v_addc_co_u32_e32 v19, vcc, 0, v17, vcc
	v_add_co_u32_e32 v16, vcc, 0x4ce0000, v16
	s_nop 1
	v_addc_co_u32_e32 v17, vcc, 0, v17, vcc
	v_add_co_u32_e32 v32, vcc, 0x4080000, v36
	global_load_dwordx4 v[28:31], v[18:19], off offset:128
	s_nop 0
	global_load_dwordx4 v[16:19], v[16:17], off offset:128
	v_addc_co_u32_e32 v33, vcc, 0, v37, vcc
	v_add_co_u32_e32 v34, vcc, 0x40a0000, v36
	s_nop 1
	v_addc_co_u32_e32 v35, vcc, 0, v37, vcc
	v_add_co_u32_e32 v38, vcc, 0x40c0000, v36
	global_load_dwordx4 v[44:47], v[32:33], off offset:128
	s_nop 0
	global_load_dwordx4 v[32:35], v[34:35], off offset:128
	v_addc_co_u32_e32 v39, vcc, 0, v37, vcc
	v_add_co_u32_e32 v36, vcc, 0x40e0000, v36
	s_nop 1
	v_addc_co_u32_e32 v37, vcc, 0, v37, vcc
	global_load_dwordx4 v[40:43], v[38:39], off offset:128
	s_nop 0
	global_load_dwordx4 v[36:39], v[36:37], off offset:128
	s_branch .LBB0_1072
